# GEMM K-loops: loop-counter/pointer SALU block moved in front of the iteration-closing s_barrier (back-edge rotation, only the branch stays behind the barrier)
# baseline (speedup 1.0000x reference)
.LBB0_84:
	ds_read_b128 v[48:51], v177
	ds_read_b128 v[52:55], v177 offset:1024
	ds_read_b128 v[64:67], v177 offset:2048
	ds_read_b128 v[68:71], v177 offset:3072
	ds_read_b128 v[144:147], v178
	ds_read_b128 v[148:151], v178 offset:1024
	ds_read_b128 v[168:171], v178 offset:2048
	ds_read_b128 v[180:183], v178 offset:3072
	s_add_u32 s24, s0, 0xfffc0080
	s_addc_u32 s25, s1, -1
	s_cmp_eq_u32 s44, 12
	s_cselect_b32 s27, s5, s25
	s_cselect_b32 s26, s17, s24
	s_cselect_b32 s25, s15, s43
	s_cselect_b32 s24, s23, s42
	v_lshl_add_u64 v[172:173], s[0:1], 0, v[160:161]
	s_add_i32 m0, s29, 0xc000
	ds_read_b128 v[188:191], v179
	ds_read_b128 v[192:195], v179 offset:1024
	ds_read_b128 v[196:199], v179 offset:2048
	ds_read_b128 v[200:203], v179 offset:3072
	ds_read_b128 v[204:207], v179 offset:4096
	ds_read_b128 v[208:211], v179 offset:5120
	ds_read_b128 v[212:215], v179 offset:6144
	ds_read_b128 v[216:219], v179 offset:7168
	global_load_lds_dwordx4 v[172:173], off
	v_lshl_add_u64 v[172:173], s[0:1], 0, v[162:163]
	s_add_i32 m0, s29, 0xe000
	s_nop 0
	global_load_lds_dwordx4 v[172:173], off
	s_waitcnt vmcnt(8)
	s_waitcnt lgkmcnt(0)
	s_barrier
	s_setprio 1
	s_waitcnt lgkmcnt(0)
	v_mfma_f32_16x16x32_bf16 v[140:143], v[48:51], v[188:191], v[140:143]
	v_mfma_f32_16x16x32_bf16 v[136:139], v[64:67], v[188:191], v[136:139]
	v_mfma_f32_16x16x32_bf16 v[124:127], v[48:51], v[196:199], v[124:127]
	v_mfma_f32_16x16x32_bf16 v[120:123], v[64:67], v[196:199], v[120:123]
	v_mfma_f32_16x16x32_bf16 v[108:111], v[48:51], v[204:207], v[108:111]
	v_mfma_f32_16x16x32_bf16 v[104:107], v[64:67], v[204:207], v[104:107]
	v_mfma_f32_16x16x32_bf16 v[92:95], v[48:51], v[212:215], v[92:95]
	v_mfma_f32_16x16x32_bf16 v[88:91], v[64:67], v[212:215], v[88:91]
	v_mfma_f32_16x16x32_bf16 v[140:143], v[52:55], v[192:195], v[140:143]
	v_mfma_f32_16x16x32_bf16 v[136:139], v[68:71], v[192:195], v[136:139]
	v_mfma_f32_16x16x32_bf16 v[124:127], v[52:55], v[200:203], v[124:127]
	v_mfma_f32_16x16x32_bf16 v[120:123], v[68:71], v[200:203], v[120:123]
	v_mfma_f32_16x16x32_bf16 v[108:111], v[52:55], v[208:211], v[108:111]
	v_mfma_f32_16x16x32_bf16 v[104:107], v[68:71], v[208:211], v[104:107]
	v_mfma_f32_16x16x32_bf16 v[92:95], v[52:55], v[216:219], v[92:95]
	v_mfma_f32_16x16x32_bf16 v[88:91], v[68:71], v[216:219], v[88:91]
	s_setprio 0
	s_setprio 1
	v_mfma_f32_16x16x32_bf16 v[132:135], v[144:147], v[188:191], v[132:135]
	v_mfma_f32_16x16x32_bf16 v[128:131], v[168:171], v[188:191], v[128:131]
	v_mfma_f32_16x16x32_bf16 v[116:119], v[144:147], v[196:199], v[116:119]
	v_mfma_f32_16x16x32_bf16 v[112:115], v[168:171], v[196:199], v[112:115]
	v_mfma_f32_16x16x32_bf16 v[100:103], v[144:147], v[204:207], v[100:103]
	v_mfma_f32_16x16x32_bf16 v[96:99], v[168:171], v[204:207], v[96:99]
	v_mfma_f32_16x16x32_bf16 v[84:87], v[144:147], v[212:215], v[84:87]
	v_mfma_f32_16x16x32_bf16 v[80:83], v[168:171], v[212:215], v[80:83]
	v_mfma_f32_16x16x32_bf16 v[132:135], v[148:151], v[192:195], v[132:135]
	v_mfma_f32_16x16x32_bf16 v[128:131], v[180:183], v[192:195], v[128:131]
	v_mfma_f32_16x16x32_bf16 v[116:119], v[148:151], v[200:203], v[116:119]
	v_mfma_f32_16x16x32_bf16 v[112:115], v[180:183], v[200:203], v[112:115]
	v_mfma_f32_16x16x32_bf16 v[100:103], v[148:151], v[208:211], v[100:103]
	v_mfma_f32_16x16x32_bf16 v[96:99], v[180:183], v[208:211], v[96:99]
	v_mfma_f32_16x16x32_bf16 v[84:87], v[148:151], v[216:219], v[84:87]
	v_mfma_f32_16x16x32_bf16 v[80:83], v[180:183], v[216:219], v[80:83]
	s_setprio 0
	s_barrier
	s_add_i32 s45, s40, s28
	v_lshl_add_u64 v[172:173], s[24:25], 0, v[154:155]
	s_mov_b32 m0, s45
	ds_read_b128 v[188:191], v179 offset:16384
	ds_read_b128 v[192:195], v179 offset:17408
	ds_read_b128 v[196:199], v179 offset:18432
	ds_read_b128 v[200:203], v179 offset:19456
	ds_read_b128 v[204:207], v179 offset:20480
	ds_read_b128 v[208:211], v179 offset:21504
	ds_read_b128 v[212:215], v179 offset:22528
	ds_read_b128 v[216:219], v179 offset:23552
	global_load_lds_dwordx4 v[172:173], off
	s_add_i32 m0, s45, 0x2000
	s_add_u32 s48, s24, 0x40000
	v_lshl_add_u64 v[220:221], s[24:25], 0, v[158:159]
	s_addc_u32 s49, s25, 0
	s_add_i32 s45, s41, s28
	global_load_lds_dwordx4 v[220:221], off
	v_lshl_add_u64 v[222:223], s[48:49], 0, v[154:155]
	s_mov_b32 m0, s45
	v_lshl_add_u64 v[224:225], s[26:27], 0, v[156:157]
	global_load_lds_dwordx4 v[222:223], off
	v_lshl_add_u64 v[222:223], s[48:49], 0, v[158:159]
	s_add_i32 m0, s45, 0x2000
	s_nop 0
	global_load_lds_dwordx4 v[222:223], off
	v_lshl_add_u64 v[222:223], s[26:27], 0, v[152:153]
	s_mov_b32 m0, s29
	s_nop 0
	global_load_lds_dwordx4 v[222:223], off
	s_mov_b32 m0, s30
	s_nop 0
	global_load_lds_dwordx4 v[224:225], off
	s_waitcnt vmcnt(8)
	s_waitcnt lgkmcnt(0)
	s_barrier
	s_setprio 1
	s_waitcnt lgkmcnt(0)
	v_mfma_f32_16x16x32_bf16 v[76:79], v[48:51], v[188:191], v[76:79]
	v_mfma_f32_16x16x32_bf16 v[72:75], v[64:67], v[188:191], v[72:75]
	v_mfma_f32_16x16x32_bf16 v[44:47], v[48:51], v[196:199], v[44:47]
	v_mfma_f32_16x16x32_bf16 v[40:43], v[64:67], v[196:199], v[40:43]
	v_mfma_f32_16x16x32_bf16 v[28:31], v[48:51], v[204:207], v[28:31]
	v_mfma_f32_16x16x32_bf16 v[24:27], v[64:67], v[204:207], v[24:27]
	v_mfma_f32_16x16x32_bf16 v[12:15], v[48:51], v[212:215], v[12:15]
	v_mfma_f32_16x16x32_bf16 v[8:11], v[64:67], v[212:215], v[8:11]
	v_mfma_f32_16x16x32_bf16 v[76:79], v[52:55], v[192:195], v[76:79]
	v_mfma_f32_16x16x32_bf16 v[72:75], v[68:71], v[192:195], v[72:75]
	v_mfma_f32_16x16x32_bf16 v[44:47], v[52:55], v[200:203], v[44:47]
	v_mfma_f32_16x16x32_bf16 v[40:43], v[68:71], v[200:203], v[40:43]
	v_mfma_f32_16x16x32_bf16 v[28:31], v[52:55], v[208:211], v[28:31]
	v_mfma_f32_16x16x32_bf16 v[24:27], v[68:71], v[208:211], v[24:27]
	v_mfma_f32_16x16x32_bf16 v[12:15], v[52:55], v[216:219], v[12:15]
	v_mfma_f32_16x16x32_bf16 v[8:11], v[68:71], v[216:219], v[8:11]
	s_setprio 0
	s_setprio 1
	v_mfma_f32_16x16x32_bf16 v[36:39], v[144:147], v[196:199], v[36:39]
	v_mfma_f32_16x16x32_bf16 v[32:35], v[168:171], v[196:199], v[32:35]
	v_mfma_f32_16x16x32_bf16 v[20:23], v[144:147], v[204:207], v[20:23]
	v_mfma_f32_16x16x32_bf16 v[16:19], v[168:171], v[204:207], v[16:19]
	v_mfma_f32_16x16x32_bf16 v[4:7], v[144:147], v[212:215], v[4:7]
	v_mfma_f32_16x16x32_bf16 v[0:3], v[168:171], v[212:215], v[0:3]
	v_mfma_f32_16x16x32_bf16 v[48:51], v[144:147], v[188:191], v[60:63]
	v_mfma_f32_16x16x32_bf16 v[52:55], v[168:171], v[188:191], v[56:59]
	v_mfma_f32_16x16x32_bf16 v[36:39], v[148:151], v[200:203], v[36:39]
	v_mfma_f32_16x16x32_bf16 v[32:35], v[180:183], v[200:203], v[32:35]
	v_mfma_f32_16x16x32_bf16 v[20:23], v[148:151], v[208:211], v[20:23]
	v_mfma_f32_16x16x32_bf16 v[16:19], v[180:183], v[208:211], v[16:19]
	v_mfma_f32_16x16x32_bf16 v[4:7], v[148:151], v[216:219], v[4:7]
	v_mfma_f32_16x16x32_bf16 v[0:3], v[180:183], v[216:219], v[0:3]
	v_mfma_f32_16x16x32_bf16 v[48:51], v[148:151], v[192:195], v[48:51]
	v_mfma_f32_16x16x32_bf16 v[52:55], v[180:183], v[192:195], v[52:55]
	s_setprio 0
	s_barrier
	s_add_i32 s45, 0, 0x18000
	s_add_i32 s48, 0, 0x1c000
	v_add_u32_e32 v68, s45, v175
	v_add_u32_e32 v180, s48, v175
	ds_read_b128 v[56:59], v68
	ds_read_b128 v[60:63], v68 offset:1024
	ds_read_b128 v[64:67], v68 offset:2048
	ds_read_b128 v[68:71], v68 offset:3072
	ds_read_b128 v[144:147], v180
	ds_read_b128 v[148:151], v180 offset:1024
	ds_read_b128 v[168:171], v180 offset:2048
	ds_read_b128 v[180:183], v180 offset:3072
	s_add_u32 s26, s26, 0x40000
	s_addc_u32 s27, s27, 0
	s_mov_b32 m0, s31
	v_lshl_add_u64 v[226:227], s[26:27], 0, v[152:153]
	ds_read_b128 v[188:191], v179 offset:32768
	ds_read_b128 v[192:195], v179 offset:33792
	ds_read_b128 v[196:199], v179 offset:34816
	ds_read_b128 v[200:203], v179 offset:35840
	ds_read_b128 v[204:207], v179 offset:36864
	ds_read_b128 v[208:211], v179 offset:37888
	ds_read_b128 v[212:215], v179 offset:38912
	ds_read_b128 v[216:219], v179 offset:39936
	global_load_lds_dwordx4 v[226:227], off
	v_lshl_add_u64 v[226:227], s[26:27], 0, v[156:157]
	s_mov_b32 m0, s34
	s_nop 0
	global_load_lds_dwordx4 v[226:227], off
	s_waitcnt vmcnt(8)
	s_waitcnt lgkmcnt(0)
	s_barrier
	s_setprio 1
	s_waitcnt lgkmcnt(0)
	v_mfma_f32_16x16x32_bf16 v[140:143], v[56:59], v[188:191], v[140:143]
	v_mfma_f32_16x16x32_bf16 v[136:139], v[64:67], v[188:191], v[136:139]
	v_mfma_f32_16x16x32_bf16 v[124:127], v[56:59], v[196:199], v[124:127]
	v_mfma_f32_16x16x32_bf16 v[120:123], v[64:67], v[196:199], v[120:123]
	v_mfma_f32_16x16x32_bf16 v[108:111], v[56:59], v[204:207], v[108:111]
	v_mfma_f32_16x16x32_bf16 v[104:107], v[64:67], v[204:207], v[104:107]
	v_mfma_f32_16x16x32_bf16 v[92:95], v[56:59], v[212:215], v[92:95]
	v_mfma_f32_16x16x32_bf16 v[88:91], v[64:67], v[212:215], v[88:91]
	v_mfma_f32_16x16x32_bf16 v[140:143], v[60:63], v[192:195], v[140:143]
	v_mfma_f32_16x16x32_bf16 v[136:139], v[68:71], v[192:195], v[136:139]
	v_mfma_f32_16x16x32_bf16 v[124:127], v[60:63], v[200:203], v[124:127]
	v_mfma_f32_16x16x32_bf16 v[120:123], v[68:71], v[200:203], v[120:123]
	v_mfma_f32_16x16x32_bf16 v[108:111], v[60:63], v[208:211], v[108:111]
	v_mfma_f32_16x16x32_bf16 v[104:107], v[68:71], v[208:211], v[104:107]
	v_mfma_f32_16x16x32_bf16 v[92:95], v[60:63], v[216:219], v[92:95]
	v_mfma_f32_16x16x32_bf16 v[88:91], v[68:71], v[216:219], v[88:91]
	s_setprio 0
	s_setprio 1
	v_mfma_f32_16x16x32_bf16 v[132:135], v[144:147], v[188:191], v[132:135]
	v_mfma_f32_16x16x32_bf16 v[128:131], v[168:171], v[188:191], v[128:131]
	v_mfma_f32_16x16x32_bf16 v[116:119], v[144:147], v[196:199], v[116:119]
	v_mfma_f32_16x16x32_bf16 v[112:115], v[168:171], v[196:199], v[112:115]
	v_mfma_f32_16x16x32_bf16 v[100:103], v[144:147], v[204:207], v[100:103]
	v_mfma_f32_16x16x32_bf16 v[96:99], v[168:171], v[204:207], v[96:99]
	v_mfma_f32_16x16x32_bf16 v[84:87], v[144:147], v[212:215], v[84:87]
	v_mfma_f32_16x16x32_bf16 v[80:83], v[168:171], v[212:215], v[80:83]
	v_mfma_f32_16x16x32_bf16 v[132:135], v[148:151], v[192:195], v[132:135]
	v_mfma_f32_16x16x32_bf16 v[128:131], v[180:183], v[192:195], v[128:131]
	v_mfma_f32_16x16x32_bf16 v[116:119], v[148:151], v[200:203], v[116:119]
	v_mfma_f32_16x16x32_bf16 v[112:115], v[180:183], v[200:203], v[112:115]
	v_mfma_f32_16x16x32_bf16 v[100:103], v[148:151], v[208:211], v[100:103]
	v_mfma_f32_16x16x32_bf16 v[96:99], v[180:183], v[208:211], v[96:99]
	v_mfma_f32_16x16x32_bf16 v[84:87], v[148:151], v[216:219], v[84:87]
	v_mfma_f32_16x16x32_bf16 v[80:83], v[180:183], v[216:219], v[80:83]
	s_setprio 0
	s_barrier
	s_add_i32 s26, s45, s28
	v_lshl_add_u64 v[172:173], v[172:173], 0, s[8:9]
	s_mov_b32 m0, s26
	ds_read_b128 v[188:191], v179 offset:49152
	ds_read_b128 v[192:195], v179 offset:50176
	ds_read_b128 v[196:199], v179 offset:51200
	ds_read_b128 v[200:203], v179 offset:52224
	ds_read_b128 v[204:207], v179 offset:53248
	ds_read_b128 v[208:211], v179 offset:54272
	ds_read_b128 v[212:215], v179 offset:55296
	ds_read_b128 v[216:219], v179 offset:56320
	global_load_lds_dwordx4 v[172:173], off
	s_add_i32 m0, s26, 0x2000
	s_add_u32 s24, s24, 0x40080
	v_lshl_add_u64 v[172:173], v[220:221], 0, s[8:9]
	s_addc_u32 s25, s25, 0
	s_add_i32 s26, s48, s28
	global_load_lds_dwordx4 v[172:173], off
	v_lshl_add_u64 v[172:173], s[24:25], 0, v[154:155]
	s_mov_b32 m0, s26
	s_nop 0
	global_load_lds_dwordx4 v[172:173], off
	v_lshl_add_u64 v[172:173], s[24:25], 0, v[158:159]
	s_add_i32 m0, s26, 0x2000
	s_nop 0
	global_load_lds_dwordx4 v[172:173], off
	v_lshl_add_u64 v[172:173], v[222:223], 0, s[8:9]
	s_mov_b32 m0, s36
	s_nop 0
	global_load_lds_dwordx4 v[172:173], off
	v_lshl_add_u64 v[172:173], v[224:225], 0, s[8:9]
	s_mov_b32 m0, s37
	s_nop 0
	global_load_lds_dwordx4 v[172:173], off
	s_waitcnt vmcnt(8)
	s_waitcnt lgkmcnt(0)
	s_barrier
	s_setprio 1
	s_waitcnt lgkmcnt(0)
	v_mfma_f32_16x16x32_bf16 v[76:79], v[56:59], v[188:191], v[76:79]
	v_mfma_f32_16x16x32_bf16 v[72:75], v[64:67], v[188:191], v[72:75]
	v_mfma_f32_16x16x32_bf16 v[44:47], v[56:59], v[196:199], v[44:47]
	v_mfma_f32_16x16x32_bf16 v[40:43], v[64:67], v[196:199], v[40:43]
	v_mfma_f32_16x16x32_bf16 v[28:31], v[56:59], v[204:207], v[28:31]
	v_mfma_f32_16x16x32_bf16 v[24:27], v[64:67], v[204:207], v[24:27]
	v_mfma_f32_16x16x32_bf16 v[12:15], v[56:59], v[212:215], v[12:15]
	v_mfma_f32_16x16x32_bf16 v[8:11], v[64:67], v[212:215], v[8:11]
	v_mfma_f32_16x16x32_bf16 v[76:79], v[60:63], v[192:195], v[76:79]
	v_mfma_f32_16x16x32_bf16 v[72:75], v[68:71], v[192:195], v[72:75]
	v_mfma_f32_16x16x32_bf16 v[44:47], v[60:63], v[200:203], v[44:47]
	v_mfma_f32_16x16x32_bf16 v[40:43], v[68:71], v[200:203], v[40:43]
	v_mfma_f32_16x16x32_bf16 v[28:31], v[60:63], v[208:211], v[28:31]
	v_mfma_f32_16x16x32_bf16 v[24:27], v[68:71], v[208:211], v[24:27]
	v_mfma_f32_16x16x32_bf16 v[12:15], v[60:63], v[216:219], v[12:15]
	v_mfma_f32_16x16x32_bf16 v[8:11], v[68:71], v[216:219], v[8:11]
	s_setprio 0
	s_setprio 1
	v_mfma_f32_16x16x32_bf16 v[48:51], v[144:147], v[188:191], v[48:51]
	v_mfma_f32_16x16x32_bf16 v[60:63], v[148:151], v[192:195], v[48:51]
	v_mfma_f32_16x16x32_bf16 v[48:51], v[168:171], v[188:191], v[52:55]
	v_mfma_f32_16x16x32_bf16 v[36:39], v[144:147], v[196:199], v[36:39]
	v_mfma_f32_16x16x32_bf16 v[32:35], v[168:171], v[196:199], v[32:35]
	v_mfma_f32_16x16x32_bf16 v[20:23], v[144:147], v[204:207], v[20:23]
	v_mfma_f32_16x16x32_bf16 v[16:19], v[168:171], v[204:207], v[16:19]
	v_mfma_f32_16x16x32_bf16 v[4:7], v[144:147], v[212:215], v[4:7]
	v_mfma_f32_16x16x32_bf16 v[0:3], v[168:171], v[212:215], v[0:3]
	v_mfma_f32_16x16x32_bf16 v[56:59], v[180:183], v[192:195], v[48:51]
	v_mfma_f32_16x16x32_bf16 v[36:39], v[148:151], v[200:203], v[36:39]
	v_mfma_f32_16x16x32_bf16 v[32:35], v[180:183], v[200:203], v[32:35]
	v_mfma_f32_16x16x32_bf16 v[20:23], v[148:151], v[208:211], v[20:23]
	v_mfma_f32_16x16x32_bf16 v[16:19], v[180:183], v[208:211], v[16:19]
	v_mfma_f32_16x16x32_bf16 v[4:7], v[148:151], v[216:219], v[4:7]
	v_mfma_f32_16x16x32_bf16 v[0:3], v[180:183], v[216:219], v[0:3]
	s_setprio 0
	s_add_i32 s44, s44, 2
	s_add_u32 s0, s0, 0x100
	s_addc_u32 s1, s1, 0
	s_add_u32 s42, s42, 0x100
	s_addc_u32 s43, s43, 0
	s_cmp_gt_u32 s44, 13
	s_barrier
	s_cbranch_scc0 .LBB0_84
	s_and_b64 vcc, exec, s[10:11]
	s_cbranch_vccz .LBB0_87
	s_barrier

.LBB0_297:
	ds_read_b128 v[156:159], v153
	ds_read_b128 v[160:163], v153 offset:1024
	ds_read_b128 v[164:167], v153 offset:2048
	ds_read_b128 v[168:171], v153 offset:3072
	ds_read_b128 v[172:175], v154
	ds_read_b128 v[176:179], v154 offset:1024
	ds_read_b128 v[180:183], v154 offset:2048
	ds_read_b128 v[188:191], v154 offset:3072
	s_add_u32 s22, s20, 0xfffc0080
	s_addc_u32 s23, s21, -1
	s_cmp_eq_u32 s52, 12
	s_cselect_b32 s25, s15, s23
	s_cselect_b32 s24, s48, s22
	s_cselect_b32 s23, s13, s51
	s_cselect_b32 s22, s49, s50
	v_lshl_add_u64 v[140:141], s[20:21], 0, v[136:137]
	s_add_i32 m0, s31, 0xc000
	ds_read_b128 v[192:195], v155
	ds_read_b128 v[196:199], v155 offset:1024
	ds_read_b128 v[200:203], v155 offset:2048
	ds_read_b128 v[204:207], v155 offset:3072
	ds_read_b128 v[208:211], v155 offset:4096
	ds_read_b128 v[212:215], v155 offset:5120
	ds_read_b128 v[216:219], v155 offset:6144
	ds_read_b128 v[220:223], v155 offset:7168
	global_load_lds_dwordx4 v[140:141], off
	v_lshl_add_u64 v[140:141], s[20:21], 0, v[138:139]
	s_add_i32 m0, s31, 0xe000
	s_nop 0
	global_load_lds_dwordx4 v[140:141], off
	s_waitcnt vmcnt(8)
	s_waitcnt lgkmcnt(0)
	s_barrier
	s_setprio 1
	s_waitcnt lgkmcnt(0)
	v_mfma_f32_16x16x32_bf16 v[124:127], v[156:159], v[192:195], v[124:127]
	v_mfma_f32_16x16x32_bf16 v[120:123], v[164:167], v[192:195], v[120:123]
	v_mfma_f32_16x16x32_bf16 v[116:119], v[156:159], v[200:203], v[116:119]
	v_mfma_f32_16x16x32_bf16 v[108:111], v[164:167], v[200:203], v[108:111]
	v_mfma_f32_16x16x32_bf16 v[100:103], v[156:159], v[208:211], v[100:103]
	v_mfma_f32_16x16x32_bf16 v[92:95], v[164:167], v[208:211], v[92:95]
	v_mfma_f32_16x16x32_bf16 v[84:87], v[156:159], v[216:219], v[84:87]
	v_mfma_f32_16x16x32_bf16 v[76:79], v[164:167], v[216:219], v[76:79]
	v_mfma_f32_16x16x32_bf16 v[124:127], v[160:163], v[196:199], v[124:127]
	v_mfma_f32_16x16x32_bf16 v[120:123], v[168:171], v[196:199], v[120:123]
	v_mfma_f32_16x16x32_bf16 v[116:119], v[160:163], v[204:207], v[116:119]
	v_mfma_f32_16x16x32_bf16 v[108:111], v[168:171], v[204:207], v[108:111]
	v_mfma_f32_16x16x32_bf16 v[100:103], v[160:163], v[212:215], v[100:103]
	v_mfma_f32_16x16x32_bf16 v[92:95], v[168:171], v[212:215], v[92:95]
	v_mfma_f32_16x16x32_bf16 v[84:87], v[160:163], v[220:223], v[84:87]
	v_mfma_f32_16x16x32_bf16 v[76:79], v[168:171], v[220:223], v[76:79]
	s_setprio 0
	s_setprio 1
	v_mfma_f32_16x16x32_bf16 v[112:115], v[172:175], v[192:195], v[112:115]
	v_mfma_f32_16x16x32_bf16 v[104:107], v[180:183], v[192:195], v[104:107]
	v_mfma_f32_16x16x32_bf16 v[96:99], v[172:175], v[200:203], v[96:99]
	v_mfma_f32_16x16x32_bf16 v[88:91], v[180:183], v[200:203], v[88:91]
	v_mfma_f32_16x16x32_bf16 v[80:83], v[172:175], v[208:211], v[80:83]
	v_mfma_f32_16x16x32_bf16 v[72:75], v[180:183], v[208:211], v[72:75]
	v_mfma_f32_16x16x32_bf16 v[68:71], v[172:175], v[216:219], v[68:71]
	v_mfma_f32_16x16x32_bf16 v[64:67], v[180:183], v[216:219], v[64:67]
	v_mfma_f32_16x16x32_bf16 v[112:115], v[176:179], v[196:199], v[112:115]
	v_mfma_f32_16x16x32_bf16 v[104:107], v[188:191], v[196:199], v[104:107]
	v_mfma_f32_16x16x32_bf16 v[96:99], v[176:179], v[204:207], v[96:99]
	v_mfma_f32_16x16x32_bf16 v[88:91], v[188:191], v[204:207], v[88:91]
	v_mfma_f32_16x16x32_bf16 v[80:83], v[176:179], v[212:215], v[80:83]
	v_mfma_f32_16x16x32_bf16 v[72:75], v[188:191], v[212:215], v[72:75]
	v_mfma_f32_16x16x32_bf16 v[68:71], v[176:179], v[220:223], v[68:71]
	v_mfma_f32_16x16x32_bf16 v[64:67], v[188:191], v[220:223], v[64:67]
	s_setprio 0
	s_barrier
	s_add_i32 s53, s42, s30
	v_lshl_add_u64 v[140:141], s[22:23], 0, v[130:131]
	s_mov_b32 m0, s53
	ds_read_b128 v[192:195], v155 offset:16384
	ds_read_b128 v[196:199], v155 offset:17408
	ds_read_b128 v[200:203], v155 offset:18432
	ds_read_b128 v[204:207], v155 offset:19456
	ds_read_b128 v[208:211], v155 offset:20480
	ds_read_b128 v[212:215], v155 offset:21504
	ds_read_b128 v[216:219], v155 offset:22528
	ds_read_b128 v[220:223], v155 offset:23552
	global_load_lds_dwordx4 v[140:141], off
	s_add_i32 m0, s53, 0x2000
	s_add_u32 s54, s22, 0x40000
	v_lshl_add_u64 v[224:225], s[22:23], 0, v[134:135]
	s_addc_u32 s55, s23, 0
	s_add_i32 s53, s43, s30
	global_load_lds_dwordx4 v[224:225], off
	v_lshl_add_u64 v[226:227], s[54:55], 0, v[130:131]
	s_mov_b32 m0, s53
	v_lshl_add_u64 v[228:229], s[24:25], 0, v[132:133]
	global_load_lds_dwordx4 v[226:227], off
	v_lshl_add_u64 v[226:227], s[54:55], 0, v[134:135]
	s_add_i32 m0, s53, 0x2000
	s_nop 0
	global_load_lds_dwordx4 v[226:227], off
	v_lshl_add_u64 v[226:227], s[24:25], 0, v[128:129]
	s_mov_b32 m0, s31
	s_nop 0
	global_load_lds_dwordx4 v[226:227], off
	s_mov_b32 m0, s36
	s_nop 0
	global_load_lds_dwordx4 v[228:229], off
	s_waitcnt vmcnt(8)
	s_waitcnt lgkmcnt(0)
	s_barrier
	s_setprio 1
	s_waitcnt lgkmcnt(0)
	v_mfma_f32_16x16x32_bf16 v[60:63], v[156:159], v[192:195], v[60:63]
	v_mfma_f32_16x16x32_bf16 v[56:59], v[164:167], v[192:195], v[56:59]
	v_mfma_f32_16x16x32_bf16 v[52:55], v[156:159], v[200:203], v[52:55]
	v_mfma_f32_16x16x32_bf16 v[44:47], v[164:167], v[200:203], v[44:47]
	v_mfma_f32_16x16x32_bf16 v[36:39], v[156:159], v[208:211], v[36:39]
	v_mfma_f32_16x16x32_bf16 v[28:31], v[164:167], v[208:211], v[28:31]
	v_mfma_f32_16x16x32_bf16 v[20:23], v[156:159], v[216:219], v[20:23]
	v_mfma_f32_16x16x32_bf16 v[12:15], v[164:167], v[216:219], v[12:15]
	v_mfma_f32_16x16x32_bf16 v[60:63], v[160:163], v[196:199], v[60:63]
	v_mfma_f32_16x16x32_bf16 v[56:59], v[168:171], v[196:199], v[56:59]
	v_mfma_f32_16x16x32_bf16 v[52:55], v[160:163], v[204:207], v[52:55]
	v_mfma_f32_16x16x32_bf16 v[44:47], v[168:171], v[204:207], v[44:47]
	v_mfma_f32_16x16x32_bf16 v[36:39], v[160:163], v[212:215], v[36:39]
	v_mfma_f32_16x16x32_bf16 v[28:31], v[168:171], v[212:215], v[28:31]
	v_mfma_f32_16x16x32_bf16 v[20:23], v[160:163], v[220:223], v[20:23]
	v_mfma_f32_16x16x32_bf16 v[12:15], v[168:171], v[220:223], v[12:15]
	s_setprio 0
	s_setprio 1
	v_mfma_f32_16x16x32_bf16 v[48:51], v[172:175], v[192:195], v[48:51]
	v_mfma_f32_16x16x32_bf16 v[40:43], v[180:183], v[192:195], v[40:43]
	v_mfma_f32_16x16x32_bf16 v[32:35], v[172:175], v[200:203], v[32:35]
	v_mfma_f32_16x16x32_bf16 v[24:27], v[180:183], v[200:203], v[24:27]
	v_mfma_f32_16x16x32_bf16 v[16:19], v[172:175], v[208:211], v[16:19]
	v_mfma_f32_16x16x32_bf16 v[8:11], v[180:183], v[208:211], v[8:11]
	v_mfma_f32_16x16x32_bf16 v[4:7], v[172:175], v[216:219], v[4:7]
	v_mfma_f32_16x16x32_bf16 v[0:3], v[180:183], v[216:219], v[0:3]
	v_mfma_f32_16x16x32_bf16 v[48:51], v[176:179], v[196:199], v[48:51]
	v_mfma_f32_16x16x32_bf16 v[40:43], v[188:191], v[196:199], v[40:43]
	v_mfma_f32_16x16x32_bf16 v[32:35], v[176:179], v[204:207], v[32:35]
	v_mfma_f32_16x16x32_bf16 v[24:27], v[188:191], v[204:207], v[24:27]
	v_mfma_f32_16x16x32_bf16 v[16:19], v[176:179], v[212:215], v[16:19]
	v_mfma_f32_16x16x32_bf16 v[8:11], v[188:191], v[212:215], v[8:11]
	v_mfma_f32_16x16x32_bf16 v[4:7], v[176:179], v[220:223], v[4:7]
	v_mfma_f32_16x16x32_bf16 v[0:3], v[188:191], v[220:223], v[0:3]
	s_setprio 0
	s_barrier
	s_add_i32 s53, 0, 0x18000
	s_add_i32 s54, 0, 0x1c000
	v_add_u32_e32 v168, s53, v151
	v_add_u32_e32 v187, s54, v151
	ds_read_b128 v[156:159], v168
	ds_read_b128 v[160:163], v168 offset:1024
	ds_read_b128 v[164:167], v168 offset:2048
	ds_read_b128 v[168:171], v168 offset:3072
	ds_read_b128 v[172:175], v187
	ds_read_b128 v[176:179], v187 offset:1024
	ds_read_b128 v[180:183], v187 offset:2048
	ds_read_b128 v[188:191], v187 offset:3072
	s_add_u32 s24, s24, 0x40000
	s_addc_u32 s25, s25, 0
	s_mov_b32 m0, s37
	v_lshl_add_u64 v[230:231], s[24:25], 0, v[128:129]
	ds_read_b128 v[192:195], v155 offset:32768
	ds_read_b128 v[196:199], v155 offset:33792
	ds_read_b128 v[200:203], v155 offset:34816
	ds_read_b128 v[204:207], v155 offset:35840
	ds_read_b128 v[208:211], v155 offset:36864
	ds_read_b128 v[212:215], v155 offset:37888
	ds_read_b128 v[216:219], v155 offset:38912
	ds_read_b128 v[220:223], v155 offset:39936
	global_load_lds_dwordx4 v[230:231], off
	v_lshl_add_u64 v[230:231], s[24:25], 0, v[132:133]
	s_mov_b32 m0, s38
	s_nop 0
	global_load_lds_dwordx4 v[230:231], off
	s_waitcnt vmcnt(8)
	s_waitcnt lgkmcnt(0)
	s_barrier
	s_setprio 1
	s_waitcnt lgkmcnt(0)
	v_mfma_f32_16x16x32_bf16 v[124:127], v[156:159], v[192:195], v[124:127]
	v_mfma_f32_16x16x32_bf16 v[120:123], v[164:167], v[192:195], v[120:123]
	v_mfma_f32_16x16x32_bf16 v[116:119], v[156:159], v[200:203], v[116:119]
	v_mfma_f32_16x16x32_bf16 v[108:111], v[164:167], v[200:203], v[108:111]
	v_mfma_f32_16x16x32_bf16 v[100:103], v[156:159], v[208:211], v[100:103]
	v_mfma_f32_16x16x32_bf16 v[92:95], v[164:167], v[208:211], v[92:95]
	v_mfma_f32_16x16x32_bf16 v[84:87], v[156:159], v[216:219], v[84:87]
	v_mfma_f32_16x16x32_bf16 v[76:79], v[164:167], v[216:219], v[76:79]
	v_mfma_f32_16x16x32_bf16 v[124:127], v[160:163], v[196:199], v[124:127]
	v_mfma_f32_16x16x32_bf16 v[120:123], v[168:171], v[196:199], v[120:123]
	v_mfma_f32_16x16x32_bf16 v[116:119], v[160:163], v[204:207], v[116:119]
	v_mfma_f32_16x16x32_bf16 v[108:111], v[168:171], v[204:207], v[108:111]
	v_mfma_f32_16x16x32_bf16 v[100:103], v[160:163], v[212:215], v[100:103]
	v_mfma_f32_16x16x32_bf16 v[92:95], v[168:171], v[212:215], v[92:95]
	v_mfma_f32_16x16x32_bf16 v[84:87], v[160:163], v[220:223], v[84:87]
	v_mfma_f32_16x16x32_bf16 v[76:79], v[168:171], v[220:223], v[76:79]
	s_setprio 0
	s_setprio 1
	v_mfma_f32_16x16x32_bf16 v[112:115], v[172:175], v[192:195], v[112:115]
	v_mfma_f32_16x16x32_bf16 v[104:107], v[180:183], v[192:195], v[104:107]
	v_mfma_f32_16x16x32_bf16 v[96:99], v[172:175], v[200:203], v[96:99]
	v_mfma_f32_16x16x32_bf16 v[88:91], v[180:183], v[200:203], v[88:91]
	v_mfma_f32_16x16x32_bf16 v[80:83], v[172:175], v[208:211], v[80:83]
	v_mfma_f32_16x16x32_bf16 v[72:75], v[180:183], v[208:211], v[72:75]
	v_mfma_f32_16x16x32_bf16 v[68:71], v[172:175], v[216:219], v[68:71]
	v_mfma_f32_16x16x32_bf16 v[64:67], v[180:183], v[216:219], v[64:67]
	v_mfma_f32_16x16x32_bf16 v[112:115], v[176:179], v[196:199], v[112:115]
	v_mfma_f32_16x16x32_bf16 v[104:107], v[188:191], v[196:199], v[104:107]
	v_mfma_f32_16x16x32_bf16 v[96:99], v[176:179], v[204:207], v[96:99]
	v_mfma_f32_16x16x32_bf16 v[88:91], v[188:191], v[204:207], v[88:91]
	v_mfma_f32_16x16x32_bf16 v[80:83], v[176:179], v[212:215], v[80:83]
	v_mfma_f32_16x16x32_bf16 v[72:75], v[188:191], v[212:215], v[72:75]
	v_mfma_f32_16x16x32_bf16 v[68:71], v[176:179], v[220:223], v[68:71]
	v_mfma_f32_16x16x32_bf16 v[64:67], v[188:191], v[220:223], v[64:67]
	s_setprio 0
	s_barrier
	s_add_i32 s24, s53, s30
	v_lshl_add_u64 v[140:141], v[140:141], 0, s[6:7]
	s_mov_b32 m0, s24
	ds_read_b128 v[192:195], v155 offset:49152
	ds_read_b128 v[196:199], v155 offset:50176
	ds_read_b128 v[200:203], v155 offset:51200
	ds_read_b128 v[204:207], v155 offset:52224
	ds_read_b128 v[208:211], v155 offset:53248
	ds_read_b128 v[212:215], v155 offset:54272
	ds_read_b128 v[216:219], v155 offset:55296
	ds_read_b128 v[220:223], v155 offset:56320
	global_load_lds_dwordx4 v[140:141], off
	s_add_i32 m0, s24, 0x2000
	s_add_u32 s22, s22, 0x40080
	v_lshl_add_u64 v[140:141], v[224:225], 0, s[6:7]
	s_addc_u32 s23, s23, 0
	s_add_i32 s24, s54, s30
	global_load_lds_dwordx4 v[140:141], off
	v_lshl_add_u64 v[140:141], s[22:23], 0, v[130:131]
	s_mov_b32 m0, s24
	s_nop 0
	global_load_lds_dwordx4 v[140:141], off
	v_lshl_add_u64 v[140:141], s[22:23], 0, v[134:135]
	s_add_i32 m0, s24, 0x2000
	s_nop 0
	global_load_lds_dwordx4 v[140:141], off
	v_lshl_add_u64 v[140:141], v[226:227], 0, s[6:7]
	s_mov_b32 m0, s39
	s_nop 0
	global_load_lds_dwordx4 v[140:141], off
	v_lshl_add_u64 v[140:141], v[228:229], 0, s[6:7]
	s_mov_b32 m0, s40
	s_nop 0
	global_load_lds_dwordx4 v[140:141], off
	s_waitcnt vmcnt(8)
	s_waitcnt lgkmcnt(0)
	s_barrier
	s_setprio 1
	s_waitcnt lgkmcnt(0)
	v_mfma_f32_16x16x32_bf16 v[60:63], v[156:159], v[192:195], v[60:63]
	v_mfma_f32_16x16x32_bf16 v[56:59], v[164:167], v[192:195], v[56:59]
	v_mfma_f32_16x16x32_bf16 v[52:55], v[156:159], v[200:203], v[52:55]
	v_mfma_f32_16x16x32_bf16 v[44:47], v[164:167], v[200:203], v[44:47]
	v_mfma_f32_16x16x32_bf16 v[36:39], v[156:159], v[208:211], v[36:39]
	v_mfma_f32_16x16x32_bf16 v[28:31], v[164:167], v[208:211], v[28:31]
	v_mfma_f32_16x16x32_bf16 v[20:23], v[156:159], v[216:219], v[20:23]
	v_mfma_f32_16x16x32_bf16 v[12:15], v[164:167], v[216:219], v[12:15]
	v_mfma_f32_16x16x32_bf16 v[60:63], v[160:163], v[196:199], v[60:63]
	v_mfma_f32_16x16x32_bf16 v[56:59], v[168:171], v[196:199], v[56:59]
	v_mfma_f32_16x16x32_bf16 v[52:55], v[160:163], v[204:207], v[52:55]
	v_mfma_f32_16x16x32_bf16 v[44:47], v[168:171], v[204:207], v[44:47]
	v_mfma_f32_16x16x32_bf16 v[36:39], v[160:163], v[212:215], v[36:39]
	v_mfma_f32_16x16x32_bf16 v[28:31], v[168:171], v[212:215], v[28:31]
	v_mfma_f32_16x16x32_bf16 v[20:23], v[160:163], v[220:223], v[20:23]
	v_mfma_f32_16x16x32_bf16 v[12:15], v[168:171], v[220:223], v[12:15]
	s_setprio 0
	s_setprio 1
	v_mfma_f32_16x16x32_bf16 v[48:51], v[172:175], v[192:195], v[48:51]
	v_mfma_f32_16x16x32_bf16 v[40:43], v[180:183], v[192:195], v[40:43]
	v_mfma_f32_16x16x32_bf16 v[32:35], v[172:175], v[200:203], v[32:35]
	v_mfma_f32_16x16x32_bf16 v[24:27], v[180:183], v[200:203], v[24:27]
	v_mfma_f32_16x16x32_bf16 v[16:19], v[172:175], v[208:211], v[16:19]
	v_mfma_f32_16x16x32_bf16 v[8:11], v[180:183], v[208:211], v[8:11]
	v_mfma_f32_16x16x32_bf16 v[4:7], v[172:175], v[216:219], v[4:7]
	v_mfma_f32_16x16x32_bf16 v[0:3], v[180:183], v[216:219], v[0:3]
	v_mfma_f32_16x16x32_bf16 v[48:51], v[176:179], v[196:199], v[48:51]
	v_mfma_f32_16x16x32_bf16 v[40:43], v[188:191], v[196:199], v[40:43]
	v_mfma_f32_16x16x32_bf16 v[32:35], v[176:179], v[204:207], v[32:35]
	v_mfma_f32_16x16x32_bf16 v[24:27], v[188:191], v[204:207], v[24:27]
	v_mfma_f32_16x16x32_bf16 v[16:19], v[176:179], v[212:215], v[16:19]
	v_mfma_f32_16x16x32_bf16 v[8:11], v[188:191], v[212:215], v[8:11]
	v_mfma_f32_16x16x32_bf16 v[4:7], v[176:179], v[220:223], v[4:7]
	v_mfma_f32_16x16x32_bf16 v[0:3], v[188:191], v[220:223], v[0:3]
	s_setprio 0
	s_add_i32 s52, s52, 2
	s_add_u32 s20, s20, 0x100
	s_addc_u32 s21, s21, 0
	s_add_u32 s50, s50, 0x100
	s_addc_u32 s51, s51, 0
	s_cmp_gt_u32 s52, 13
	s_barrier
	s_cbranch_scc0 .LBB0_297
	s_and_b64 vcc, exec, s[8:9]
	s_cbranch_vccz .LBB0_300
	s_barrier

.LBB0_317:
	ds_read_b128 v[152:155], v143
	ds_read_b128 v[156:159], v143 offset:1024
	ds_read_b128 v[160:163], v143 offset:2048
	ds_read_b128 v[164:167], v143 offset:3072
	ds_read_b128 v[168:171], v144
	ds_read_b128 v[172:175], v144 offset:1024
	ds_read_b128 v[176:179], v144 offset:2048
	ds_read_b128 v[180:183], v144 offset:3072
	s_add_u32 s22, s20, 0xfffc0080
	s_addc_u32 s23, s21, -1
	s_cmp_eq_u32 s52, 12
	s_cselect_b32 s25, s15, s23
	s_cselect_b32 s24, s48, s22
	s_cselect_b32 s23, s13, s51
	s_cselect_b32 s22, s49, s50
	v_lshl_add_u64 v[140:141], s[20:21], 0, v[136:137]
	s_add_i32 m0, s31, 0xc000
	ds_read_b128 v[188:191], v145
	ds_read_b128 v[192:195], v145 offset:1024
	ds_read_b128 v[196:199], v145 offset:2048
	ds_read_b128 v[200:203], v145 offset:3072
	ds_read_b128 v[204:207], v145 offset:4096
	ds_read_b128 v[208:211], v145 offset:5120
	ds_read_b128 v[212:215], v145 offset:6144
	ds_read_b128 v[216:219], v145 offset:7168
	global_load_lds_dwordx4 v[140:141], off
	v_lshl_add_u64 v[140:141], s[20:21], 0, v[138:139]
	s_add_i32 m0, s31, 0xe000
	s_nop 0
	global_load_lds_dwordx4 v[140:141], off
	s_waitcnt vmcnt(8)
	s_waitcnt lgkmcnt(0)
	s_barrier
	s_setprio 1
	s_waitcnt lgkmcnt(0)
	v_mfma_f32_16x16x32_bf16 v[124:127], v[152:155], v[188:191], v[124:127]
	v_mfma_f32_16x16x32_bf16 v[120:123], v[160:163], v[188:191], v[120:123]
	v_mfma_f32_16x16x32_bf16 v[116:119], v[152:155], v[196:199], v[116:119]
	v_mfma_f32_16x16x32_bf16 v[108:111], v[160:163], v[196:199], v[108:111]
	v_mfma_f32_16x16x32_bf16 v[100:103], v[152:155], v[204:207], v[100:103]
	v_mfma_f32_16x16x32_bf16 v[92:95], v[160:163], v[204:207], v[92:95]
	v_mfma_f32_16x16x32_bf16 v[80:83], v[152:155], v[212:215], v[80:83]
	v_mfma_f32_16x16x32_bf16 v[72:75], v[160:163], v[212:215], v[72:75]
	v_mfma_f32_16x16x32_bf16 v[124:127], v[156:159], v[192:195], v[124:127]
	v_mfma_f32_16x16x32_bf16 v[120:123], v[164:167], v[192:195], v[120:123]
	v_mfma_f32_16x16x32_bf16 v[116:119], v[156:159], v[200:203], v[116:119]
	v_mfma_f32_16x16x32_bf16 v[108:111], v[164:167], v[200:203], v[108:111]
	v_mfma_f32_16x16x32_bf16 v[100:103], v[156:159], v[208:211], v[100:103]
	v_mfma_f32_16x16x32_bf16 v[92:95], v[164:167], v[208:211], v[92:95]
	v_mfma_f32_16x16x32_bf16 v[80:83], v[156:159], v[216:219], v[80:83]
	v_mfma_f32_16x16x32_bf16 v[72:75], v[164:167], v[216:219], v[72:75]
	s_setprio 0
	s_setprio 1
	v_mfma_f32_16x16x32_bf16 v[112:115], v[168:171], v[188:191], v[112:115]
	v_mfma_f32_16x16x32_bf16 v[104:107], v[176:179], v[188:191], v[104:107]
	v_mfma_f32_16x16x32_bf16 v[96:99], v[168:171], v[196:199], v[96:99]
	v_mfma_f32_16x16x32_bf16 v[88:91], v[176:179], v[196:199], v[88:91]
	v_mfma_f32_16x16x32_bf16 v[84:87], v[168:171], v[204:207], v[84:87]
	v_mfma_f32_16x16x32_bf16 v[76:79], v[176:179], v[204:207], v[76:79]
	v_mfma_f32_16x16x32_bf16 v[68:71], v[168:171], v[212:215], v[68:71]
	v_mfma_f32_16x16x32_bf16 v[64:67], v[176:179], v[212:215], v[64:67]
	v_mfma_f32_16x16x32_bf16 v[112:115], v[172:175], v[192:195], v[112:115]
	v_mfma_f32_16x16x32_bf16 v[104:107], v[180:183], v[192:195], v[104:107]
	v_mfma_f32_16x16x32_bf16 v[96:99], v[172:175], v[200:203], v[96:99]
	v_mfma_f32_16x16x32_bf16 v[88:91], v[180:183], v[200:203], v[88:91]
	v_mfma_f32_16x16x32_bf16 v[84:87], v[172:175], v[208:211], v[84:87]
	v_mfma_f32_16x16x32_bf16 v[76:79], v[180:183], v[208:211], v[76:79]
	v_mfma_f32_16x16x32_bf16 v[68:71], v[172:175], v[216:219], v[68:71]
	v_mfma_f32_16x16x32_bf16 v[64:67], v[180:183], v[216:219], v[64:67]
	s_setprio 0
	s_barrier
	s_add_i32 s53, s42, s30
	v_lshl_add_u64 v[140:141], s[22:23], 0, v[130:131]
	s_mov_b32 m0, s53
	ds_read_b128 v[188:191], v145 offset:16384
	ds_read_b128 v[192:195], v145 offset:17408
	ds_read_b128 v[196:199], v145 offset:18432
	ds_read_b128 v[200:203], v145 offset:19456
	ds_read_b128 v[204:207], v145 offset:20480
	ds_read_b128 v[208:211], v145 offset:21504
	ds_read_b128 v[212:215], v145 offset:22528
	ds_read_b128 v[216:219], v145 offset:23552
	global_load_lds_dwordx4 v[140:141], off
	s_add_i32 m0, s53, 0x2000
	s_add_u32 s54, s22, 0x40000
	v_lshl_add_u64 v[148:149], s[22:23], 0, v[134:135]
	s_addc_u32 s55, s23, 0
	s_add_i32 s53, s43, s30
	global_load_lds_dwordx4 v[148:149], off
	v_lshl_add_u64 v[220:221], s[54:55], 0, v[130:131]
	s_mov_b32 m0, s53
	v_lshl_add_u64 v[222:223], s[24:25], 0, v[132:133]
	global_load_lds_dwordx4 v[220:221], off
	v_lshl_add_u64 v[220:221], s[54:55], 0, v[134:135]
	s_add_i32 m0, s53, 0x2000
	s_nop 0
	global_load_lds_dwordx4 v[220:221], off
	v_lshl_add_u64 v[220:221], s[24:25], 0, v[128:129]
	s_mov_b32 m0, s31
	s_nop 0
	global_load_lds_dwordx4 v[220:221], off
	s_mov_b32 m0, s36
	s_nop 0
	global_load_lds_dwordx4 v[222:223], off
	s_waitcnt vmcnt(8)
	s_waitcnt lgkmcnt(0)
	s_barrier
	s_setprio 1
	s_waitcnt lgkmcnt(0)
	v_mfma_f32_16x16x32_bf16 v[60:63], v[152:155], v[188:191], v[60:63]
	v_mfma_f32_16x16x32_bf16 v[56:59], v[160:163], v[188:191], v[56:59]
	v_mfma_f32_16x16x32_bf16 v[52:55], v[152:155], v[196:199], v[52:55]
	v_mfma_f32_16x16x32_bf16 v[44:47], v[160:163], v[196:199], v[44:47]
	v_mfma_f32_16x16x32_bf16 v[36:39], v[152:155], v[204:207], v[36:39]
	v_mfma_f32_16x16x32_bf16 v[28:31], v[160:163], v[204:207], v[28:31]
	v_mfma_f32_16x16x32_bf16 v[20:23], v[152:155], v[212:215], v[20:23]
	v_mfma_f32_16x16x32_bf16 v[12:15], v[160:163], v[212:215], v[12:15]
	v_mfma_f32_16x16x32_bf16 v[60:63], v[156:159], v[192:195], v[60:63]
	v_mfma_f32_16x16x32_bf16 v[56:59], v[164:167], v[192:195], v[56:59]
	v_mfma_f32_16x16x32_bf16 v[52:55], v[156:159], v[200:203], v[52:55]
	v_mfma_f32_16x16x32_bf16 v[44:47], v[164:167], v[200:203], v[44:47]
	v_mfma_f32_16x16x32_bf16 v[36:39], v[156:159], v[208:211], v[36:39]
	v_mfma_f32_16x16x32_bf16 v[28:31], v[164:167], v[208:211], v[28:31]
	v_mfma_f32_16x16x32_bf16 v[20:23], v[156:159], v[216:219], v[20:23]
	v_mfma_f32_16x16x32_bf16 v[12:15], v[164:167], v[216:219], v[12:15]
	s_setprio 0
	s_setprio 1
	v_mfma_f32_16x16x32_bf16 v[48:51], v[168:171], v[188:191], v[48:51]
	v_mfma_f32_16x16x32_bf16 v[40:43], v[176:179], v[188:191], v[40:43]
	v_mfma_f32_16x16x32_bf16 v[32:35], v[168:171], v[196:199], v[32:35]
	v_mfma_f32_16x16x32_bf16 v[24:27], v[176:179], v[196:199], v[24:27]
	v_mfma_f32_16x16x32_bf16 v[16:19], v[168:171], v[204:207], v[16:19]
	v_mfma_f32_16x16x32_bf16 v[8:11], v[176:179], v[204:207], v[8:11]
	v_mfma_f32_16x16x32_bf16 v[4:7], v[168:171], v[212:215], v[4:7]
	v_mfma_f32_16x16x32_bf16 v[0:3], v[176:179], v[212:215], v[0:3]
	v_mfma_f32_16x16x32_bf16 v[48:51], v[172:175], v[192:195], v[48:51]
	v_mfma_f32_16x16x32_bf16 v[40:43], v[180:183], v[192:195], v[40:43]
	v_mfma_f32_16x16x32_bf16 v[32:35], v[172:175], v[200:203], v[32:35]
	v_mfma_f32_16x16x32_bf16 v[24:27], v[180:183], v[200:203], v[24:27]
	v_mfma_f32_16x16x32_bf16 v[16:19], v[172:175], v[208:211], v[16:19]
	v_mfma_f32_16x16x32_bf16 v[8:11], v[180:183], v[208:211], v[8:11]
	v_mfma_f32_16x16x32_bf16 v[4:7], v[172:175], v[216:219], v[4:7]
	v_mfma_f32_16x16x32_bf16 v[0:3], v[180:183], v[216:219], v[0:3]
	s_setprio 0
	s_barrier
	s_add_i32 s53, 0, 0x18000
	v_add_u32_e32 v146, s53, v142
	s_add_i32 s54, 0, 0x1c000
	ds_read_b128 v[152:155], v146
	ds_read_b128 v[156:159], v146 offset:1024
	ds_read_b128 v[160:163], v146 offset:2048
	ds_read_b128 v[164:167], v146 offset:3072
	v_add_u32_e32 v146, s54, v142
	ds_read_b128 v[168:171], v146
	ds_read_b128 v[172:175], v146 offset:1024
	ds_read_b128 v[176:179], v146 offset:2048
	ds_read_b128 v[180:183], v146 offset:3072
	s_add_u32 s24, s24, 0x40000
	s_addc_u32 s25, s25, 0
	s_mov_b32 m0, s37
	v_lshl_add_u64 v[224:225], s[24:25], 0, v[128:129]
	ds_read_b128 v[188:191], v145 offset:32768
	ds_read_b128 v[192:195], v145 offset:33792
	ds_read_b128 v[196:199], v145 offset:34816
	ds_read_b128 v[200:203], v145 offset:35840
	ds_read_b128 v[204:207], v145 offset:36864
	ds_read_b128 v[208:211], v145 offset:37888
	ds_read_b128 v[212:215], v145 offset:38912
	ds_read_b128 v[216:219], v145 offset:39936
	global_load_lds_dwordx4 v[224:225], off
	v_lshl_add_u64 v[224:225], s[24:25], 0, v[132:133]
	s_mov_b32 m0, s38
	s_nop 0
	global_load_lds_dwordx4 v[224:225], off
	s_waitcnt vmcnt(8)
	s_waitcnt lgkmcnt(0)
	s_barrier
	s_setprio 1
	s_waitcnt lgkmcnt(0)
	v_mfma_f32_16x16x32_bf16 v[124:127], v[152:155], v[188:191], v[124:127]
	v_mfma_f32_16x16x32_bf16 v[120:123], v[160:163], v[188:191], v[120:123]
	v_mfma_f32_16x16x32_bf16 v[116:119], v[152:155], v[196:199], v[116:119]
	v_mfma_f32_16x16x32_bf16 v[108:111], v[160:163], v[196:199], v[108:111]
	v_mfma_f32_16x16x32_bf16 v[100:103], v[152:155], v[204:207], v[100:103]
	v_mfma_f32_16x16x32_bf16 v[92:95], v[160:163], v[204:207], v[92:95]
	v_mfma_f32_16x16x32_bf16 v[80:83], v[152:155], v[212:215], v[80:83]
	v_mfma_f32_16x16x32_bf16 v[72:75], v[160:163], v[212:215], v[72:75]
	v_mfma_f32_16x16x32_bf16 v[124:127], v[156:159], v[192:195], v[124:127]
	v_mfma_f32_16x16x32_bf16 v[120:123], v[164:167], v[192:195], v[120:123]
	v_mfma_f32_16x16x32_bf16 v[116:119], v[156:159], v[200:203], v[116:119]
	v_mfma_f32_16x16x32_bf16 v[108:111], v[164:167], v[200:203], v[108:111]
	v_mfma_f32_16x16x32_bf16 v[100:103], v[156:159], v[208:211], v[100:103]
	v_mfma_f32_16x16x32_bf16 v[92:95], v[164:167], v[208:211], v[92:95]
	v_mfma_f32_16x16x32_bf16 v[80:83], v[156:159], v[216:219], v[80:83]
	v_mfma_f32_16x16x32_bf16 v[72:75], v[164:167], v[216:219], v[72:75]
	s_setprio 0
	s_setprio 1
	v_mfma_f32_16x16x32_bf16 v[112:115], v[168:171], v[188:191], v[112:115]
	v_mfma_f32_16x16x32_bf16 v[104:107], v[176:179], v[188:191], v[104:107]
	v_mfma_f32_16x16x32_bf16 v[96:99], v[168:171], v[196:199], v[96:99]
	v_mfma_f32_16x16x32_bf16 v[88:91], v[176:179], v[196:199], v[88:91]
	v_mfma_f32_16x16x32_bf16 v[84:87], v[168:171], v[204:207], v[84:87]
	v_mfma_f32_16x16x32_bf16 v[76:79], v[176:179], v[204:207], v[76:79]
	v_mfma_f32_16x16x32_bf16 v[68:71], v[168:171], v[212:215], v[68:71]
	v_mfma_f32_16x16x32_bf16 v[64:67], v[176:179], v[212:215], v[64:67]
	v_mfma_f32_16x16x32_bf16 v[112:115], v[172:175], v[192:195], v[112:115]
	v_mfma_f32_16x16x32_bf16 v[104:107], v[180:183], v[192:195], v[104:107]
	v_mfma_f32_16x16x32_bf16 v[96:99], v[172:175], v[200:203], v[96:99]
	v_mfma_f32_16x16x32_bf16 v[88:91], v[180:183], v[200:203], v[88:91]
	v_mfma_f32_16x16x32_bf16 v[84:87], v[172:175], v[208:211], v[84:87]
	v_mfma_f32_16x16x32_bf16 v[76:79], v[180:183], v[208:211], v[76:79]
	v_mfma_f32_16x16x32_bf16 v[68:71], v[172:175], v[216:219], v[68:71]
	v_mfma_f32_16x16x32_bf16 v[64:67], v[180:183], v[216:219], v[64:67]
	s_setprio 0
	s_barrier
	s_add_i32 s24, s53, s30
	v_lshl_add_u64 v[140:141], v[140:141], 0, s[4:5]
	s_mov_b32 m0, s24
	ds_read_b128 v[188:191], v145 offset:49152
	ds_read_b128 v[192:195], v145 offset:50176
	ds_read_b128 v[196:199], v145 offset:51200
	ds_read_b128 v[200:203], v145 offset:52224
	ds_read_b128 v[204:207], v145 offset:53248
	ds_read_b128 v[208:211], v145 offset:54272
	ds_read_b128 v[212:215], v145 offset:55296
	ds_read_b128 v[216:219], v145 offset:56320
	global_load_lds_dwordx4 v[140:141], off
	s_add_i32 m0, s24, 0x2000
	s_add_u32 s22, s22, 0x40080
	v_lshl_add_u64 v[140:141], v[148:149], 0, s[4:5]
	s_addc_u32 s23, s23, 0
	s_add_i32 s24, s54, s30
	global_load_lds_dwordx4 v[140:141], off
	v_lshl_add_u64 v[140:141], s[22:23], 0, v[130:131]
	s_mov_b32 m0, s24
	s_nop 0
	global_load_lds_dwordx4 v[140:141], off
	v_lshl_add_u64 v[140:141], s[22:23], 0, v[134:135]
	s_add_i32 m0, s24, 0x2000
	s_nop 0
	global_load_lds_dwordx4 v[140:141], off
	v_lshl_add_u64 v[140:141], v[220:221], 0, s[4:5]
	s_mov_b32 m0, s39
	s_nop 0
	global_load_lds_dwordx4 v[140:141], off
	v_lshl_add_u64 v[140:141], v[222:223], 0, s[4:5]
	s_mov_b32 m0, s40
	s_nop 0
	global_load_lds_dwordx4 v[140:141], off
	s_waitcnt vmcnt(8)
	s_waitcnt lgkmcnt(0)
	s_barrier
	s_setprio 1
	s_waitcnt lgkmcnt(0)
	v_mfma_f32_16x16x32_bf16 v[60:63], v[152:155], v[188:191], v[60:63]
	v_mfma_f32_16x16x32_bf16 v[56:59], v[160:163], v[188:191], v[56:59]
	v_mfma_f32_16x16x32_bf16 v[52:55], v[152:155], v[196:199], v[52:55]
	v_mfma_f32_16x16x32_bf16 v[44:47], v[160:163], v[196:199], v[44:47]
	v_mfma_f32_16x16x32_bf16 v[36:39], v[152:155], v[204:207], v[36:39]
	v_mfma_f32_16x16x32_bf16 v[28:31], v[160:163], v[204:207], v[28:31]
	v_mfma_f32_16x16x32_bf16 v[20:23], v[152:155], v[212:215], v[20:23]
	v_mfma_f32_16x16x32_bf16 v[12:15], v[160:163], v[212:215], v[12:15]
	v_mfma_f32_16x16x32_bf16 v[60:63], v[156:159], v[192:195], v[60:63]
	v_mfma_f32_16x16x32_bf16 v[56:59], v[164:167], v[192:195], v[56:59]
	v_mfma_f32_16x16x32_bf16 v[52:55], v[156:159], v[200:203], v[52:55]
	v_mfma_f32_16x16x32_bf16 v[44:47], v[164:167], v[200:203], v[44:47]
	v_mfma_f32_16x16x32_bf16 v[36:39], v[156:159], v[208:211], v[36:39]
	v_mfma_f32_16x16x32_bf16 v[28:31], v[164:167], v[208:211], v[28:31]
	v_mfma_f32_16x16x32_bf16 v[20:23], v[156:159], v[216:219], v[20:23]
	v_mfma_f32_16x16x32_bf16 v[12:15], v[164:167], v[216:219], v[12:15]
	s_setprio 0
	s_setprio 1
	v_mfma_f32_16x16x32_bf16 v[48:51], v[168:171], v[188:191], v[48:51]
	v_mfma_f32_16x16x32_bf16 v[40:43], v[176:179], v[188:191], v[40:43]
	v_mfma_f32_16x16x32_bf16 v[32:35], v[168:171], v[196:199], v[32:35]
	v_mfma_f32_16x16x32_bf16 v[24:27], v[176:179], v[196:199], v[24:27]
	v_mfma_f32_16x16x32_bf16 v[16:19], v[168:171], v[204:207], v[16:19]
	v_mfma_f32_16x16x32_bf16 v[8:11], v[176:179], v[204:207], v[8:11]
	v_mfma_f32_16x16x32_bf16 v[4:7], v[168:171], v[212:215], v[4:7]
	v_mfma_f32_16x16x32_bf16 v[0:3], v[176:179], v[212:215], v[0:3]
	v_mfma_f32_16x16x32_bf16 v[48:51], v[172:175], v[192:195], v[48:51]
	v_mfma_f32_16x16x32_bf16 v[40:43], v[180:183], v[192:195], v[40:43]
	v_mfma_f32_16x16x32_bf16 v[32:35], v[172:175], v[200:203], v[32:35]
	v_mfma_f32_16x16x32_bf16 v[24:27], v[180:183], v[200:203], v[24:27]
	v_mfma_f32_16x16x32_bf16 v[16:19], v[172:175], v[208:211], v[16:19]
	v_mfma_f32_16x16x32_bf16 v[8:11], v[180:183], v[208:211], v[8:11]
	v_mfma_f32_16x16x32_bf16 v[4:7], v[172:175], v[216:219], v[4:7]
	v_mfma_f32_16x16x32_bf16 v[0:3], v[180:183], v[216:219], v[0:3]
	s_setprio 0
	s_add_i32 s52, s52, 2
	s_add_u32 s20, s20, 0x100
	s_addc_u32 s21, s21, 0
	s_add_u32 s50, s50, 0x100
	s_addc_u32 s51, s51, 0
	s_cmp_gt_u32 s52, 13
	s_barrier
	s_cbranch_scc0 .LBB0_317
	s_and_b64 vcc, exec, s[6:7]
	s_cbranch_vccz .LBB0_320
	s_barrier

.LBB0_427:
	ds_read_b128 v[140:143], v147
	ds_read_b128 v[152:155], v147 offset:1024
	ds_read_b128 v[156:159], v147 offset:2048
	ds_read_b128 v[160:163], v147 offset:3072
	ds_read_b128 v[164:167], v148
	ds_read_b128 v[168:171], v148 offset:1024
	ds_read_b128 v[172:175], v148 offset:2048
	ds_read_b128 v[176:179], v148 offset:3072
	s_add_u32 s28, s26, 0xfffc0080
	s_addc_u32 s29, s27, -1
	s_cmp_eq_u32 s55, 12
	s_cselect_b32 s31, s17, s29
	s_cselect_b32 s30, s23, s28
	s_cselect_b32 s29, s15, s54
	s_cselect_b32 s28, s52, s53
	v_lshl_add_u64 v[216:217], s[26:27], 0, v[132:133]
	s_add_i32 m0, s25, 0xc000
	ds_read_b128 v[180:183], v149
	ds_read_b128 v[188:191], v149 offset:1024
	ds_read_b128 v[192:195], v149 offset:2048
	ds_read_b128 v[196:199], v149 offset:3072
	ds_read_b128 v[200:203], v149 offset:4096
	ds_read_b128 v[204:207], v149 offset:5120
	ds_read_b128 v[208:211], v149 offset:6144
	ds_read_b128 v[212:215], v149 offset:7168
	global_load_lds_dwordx4 v[216:217], off
	v_lshl_add_u64 v[216:217], s[26:27], 0, v[134:135]
	s_add_i32 m0, s25, 0xe000
	s_nop 0
	global_load_lds_dwordx4 v[216:217], off
	s_waitcnt vmcnt(8)
	s_waitcnt lgkmcnt(0)
	s_barrier
	s_setprio 1
	s_waitcnt lgkmcnt(0)
	v_mfma_f32_16x16x32_bf16 v[124:127], v[140:143], v[180:183], v[124:127]
	v_mfma_f32_16x16x32_bf16 v[120:123], v[156:159], v[180:183], v[120:123]
	v_mfma_f32_16x16x32_bf16 v[108:111], v[140:143], v[192:195], v[108:111]
	v_mfma_f32_16x16x32_bf16 v[104:107], v[156:159], v[192:195], v[104:107]
	v_mfma_f32_16x16x32_bf16 v[92:95], v[140:143], v[200:203], v[92:95]
	v_mfma_f32_16x16x32_bf16 v[88:91], v[156:159], v[200:203], v[88:91]
	v_mfma_f32_16x16x32_bf16 v[76:79], v[140:143], v[208:211], v[76:79]
	v_mfma_f32_16x16x32_bf16 v[72:75], v[156:159], v[208:211], v[72:75]
	v_mfma_f32_16x16x32_bf16 v[124:127], v[152:155], v[188:191], v[124:127]
	v_mfma_f32_16x16x32_bf16 v[120:123], v[160:163], v[188:191], v[120:123]
	v_mfma_f32_16x16x32_bf16 v[108:111], v[152:155], v[196:199], v[108:111]
	v_mfma_f32_16x16x32_bf16 v[104:107], v[160:163], v[196:199], v[104:107]
	v_mfma_f32_16x16x32_bf16 v[92:95], v[152:155], v[204:207], v[92:95]
	v_mfma_f32_16x16x32_bf16 v[88:91], v[160:163], v[204:207], v[88:91]
	v_mfma_f32_16x16x32_bf16 v[76:79], v[152:155], v[212:215], v[76:79]
	v_mfma_f32_16x16x32_bf16 v[72:75], v[160:163], v[212:215], v[72:75]
	s_setprio 0
	s_setprio 1
	v_mfma_f32_16x16x32_bf16 v[116:119], v[164:167], v[180:183], v[116:119]
	v_mfma_f32_16x16x32_bf16 v[112:115], v[172:175], v[180:183], v[112:115]
	v_mfma_f32_16x16x32_bf16 v[100:103], v[164:167], v[192:195], v[100:103]
	v_mfma_f32_16x16x32_bf16 v[96:99], v[172:175], v[192:195], v[96:99]
	v_mfma_f32_16x16x32_bf16 v[84:87], v[164:167], v[200:203], v[84:87]
	v_mfma_f32_16x16x32_bf16 v[80:83], v[172:175], v[200:203], v[80:83]
	v_mfma_f32_16x16x32_bf16 v[68:71], v[164:167], v[208:211], v[68:71]
	v_mfma_f32_16x16x32_bf16 v[64:67], v[172:175], v[208:211], v[64:67]
	v_mfma_f32_16x16x32_bf16 v[116:119], v[168:171], v[188:191], v[116:119]
	v_mfma_f32_16x16x32_bf16 v[112:115], v[176:179], v[188:191], v[112:115]
	v_mfma_f32_16x16x32_bf16 v[100:103], v[168:171], v[196:199], v[100:103]
	v_mfma_f32_16x16x32_bf16 v[96:99], v[176:179], v[196:199], v[96:99]
	v_mfma_f32_16x16x32_bf16 v[84:87], v[168:171], v[204:207], v[84:87]
	v_mfma_f32_16x16x32_bf16 v[80:83], v[176:179], v[204:207], v[80:83]
	v_mfma_f32_16x16x32_bf16 v[68:71], v[168:171], v[212:215], v[68:71]
	v_mfma_f32_16x16x32_bf16 v[64:67], v[176:179], v[212:215], v[64:67]
	s_setprio 0
	s_barrier
	s_add_i32 s56, s50, s39
	v_lshl_add_u64 v[216:217], s[28:29], 0, v[128:129]
	s_mov_b32 m0, s56
	ds_read_b128 v[180:183], v149 offset:16384
	ds_read_b128 v[188:191], v149 offset:17408
	ds_read_b128 v[192:195], v149 offset:18432
	ds_read_b128 v[196:199], v149 offset:19456
	ds_read_b128 v[200:203], v149 offset:20480
	ds_read_b128 v[204:207], v149 offset:21504
	ds_read_b128 v[208:211], v149 offset:22528
	ds_read_b128 v[212:215], v149 offset:23552
	global_load_lds_dwordx4 v[216:217], off
	s_add_i32 m0, s56, 0x2000
	s_add_u32 s56, s28, 0x40000
	v_lshl_add_u64 v[218:219], s[28:29], 0, v[130:131]
	s_addc_u32 s57, s29, 0
	s_add_i32 s58, s51, s39
	global_load_lds_dwordx4 v[218:219], off
	v_lshl_add_u64 v[220:221], s[56:57], 0, v[128:129]
	s_mov_b32 m0, s58
	v_lshl_add_u64 v[222:223], s[30:31], 0, v[130:131]
	global_load_lds_dwordx4 v[220:221], off
	v_lshl_add_u64 v[220:221], s[56:57], 0, v[130:131]
	s_add_i32 m0, s58, 0x2000
	s_nop 0
	global_load_lds_dwordx4 v[220:221], off
	v_lshl_add_u64 v[220:221], s[30:31], 0, v[128:129]
	s_mov_b32 m0, s25
	s_nop 0
	global_load_lds_dwordx4 v[220:221], off
	s_mov_b32 m0, s40
	s_nop 0
	global_load_lds_dwordx4 v[222:223], off
	s_waitcnt vmcnt(8)
	s_waitcnt lgkmcnt(0)
	s_barrier
	s_setprio 1
	s_waitcnt lgkmcnt(0)
	v_mfma_f32_16x16x32_bf16 v[60:63], v[140:143], v[180:183], v[60:63]
	v_mfma_f32_16x16x32_bf16 v[56:59], v[156:159], v[180:183], v[56:59]
	v_mfma_f32_16x16x32_bf16 v[44:47], v[140:143], v[192:195], v[44:47]
	v_mfma_f32_16x16x32_bf16 v[40:43], v[156:159], v[192:195], v[40:43]
	v_mfma_f32_16x16x32_bf16 v[28:31], v[140:143], v[200:203], v[28:31]
	v_mfma_f32_16x16x32_bf16 v[24:27], v[156:159], v[200:203], v[24:27]
	v_mfma_f32_16x16x32_bf16 v[12:15], v[140:143], v[208:211], v[12:15]
	v_mfma_f32_16x16x32_bf16 v[8:11], v[156:159], v[208:211], v[8:11]
	v_mfma_f32_16x16x32_bf16 v[60:63], v[152:155], v[188:191], v[60:63]
	v_mfma_f32_16x16x32_bf16 v[56:59], v[160:163], v[188:191], v[56:59]
	v_mfma_f32_16x16x32_bf16 v[44:47], v[152:155], v[196:199], v[44:47]
	v_mfma_f32_16x16x32_bf16 v[40:43], v[160:163], v[196:199], v[40:43]
	v_mfma_f32_16x16x32_bf16 v[28:31], v[152:155], v[204:207], v[28:31]
	v_mfma_f32_16x16x32_bf16 v[24:27], v[160:163], v[204:207], v[24:27]
	v_mfma_f32_16x16x32_bf16 v[12:15], v[152:155], v[212:215], v[12:15]
	v_mfma_f32_16x16x32_bf16 v[8:11], v[160:163], v[212:215], v[8:11]
	s_setprio 0
	s_setprio 1
	v_mfma_f32_16x16x32_bf16 v[52:55], v[164:167], v[180:183], v[52:55]
	v_mfma_f32_16x16x32_bf16 v[48:51], v[172:175], v[180:183], v[48:51]
	v_mfma_f32_16x16x32_bf16 v[36:39], v[164:167], v[192:195], v[36:39]
	v_mfma_f32_16x16x32_bf16 v[32:35], v[172:175], v[192:195], v[32:35]
	v_mfma_f32_16x16x32_bf16 v[20:23], v[164:167], v[200:203], v[20:23]
	v_mfma_f32_16x16x32_bf16 v[16:19], v[172:175], v[200:203], v[16:19]
	v_mfma_f32_16x16x32_bf16 v[4:7], v[164:167], v[208:211], v[4:7]
	v_mfma_f32_16x16x32_bf16 v[0:3], v[172:175], v[208:211], v[0:3]
	v_mfma_f32_16x16x32_bf16 v[52:55], v[168:171], v[188:191], v[52:55]
	v_mfma_f32_16x16x32_bf16 v[48:51], v[176:179], v[188:191], v[48:51]
	v_mfma_f32_16x16x32_bf16 v[36:39], v[168:171], v[196:199], v[36:39]
	v_mfma_f32_16x16x32_bf16 v[32:35], v[176:179], v[196:199], v[32:35]
	v_mfma_f32_16x16x32_bf16 v[20:23], v[168:171], v[204:207], v[20:23]
	v_mfma_f32_16x16x32_bf16 v[16:19], v[176:179], v[204:207], v[16:19]
	v_mfma_f32_16x16x32_bf16 v[4:7], v[168:171], v[212:215], v[4:7]
	v_mfma_f32_16x16x32_bf16 v[0:3], v[176:179], v[212:215], v[0:3]
	s_setprio 0
	s_barrier
	s_add_i32 s56, 0, 0x18000
	v_add_u32_e32 v151, s56, v145
	s_add_i32 s57, 0, 0x1c000
	ds_read_b128 v[140:143], v151
	ds_read_b128 v[152:155], v151 offset:1024
	ds_read_b128 v[156:159], v151 offset:2048
	ds_read_b128 v[160:163], v151 offset:3072
	v_add_u32_e32 v151, s57, v145
	ds_read_b128 v[164:167], v151
	ds_read_b128 v[168:171], v151 offset:1024
	ds_read_b128 v[172:175], v151 offset:2048
	ds_read_b128 v[176:179], v151 offset:3072
	s_add_u32 s30, s30, 0x40000
	s_addc_u32 s31, s31, 0
	s_mov_b32 m0, s41
	v_lshl_add_u64 v[224:225], s[30:31], 0, v[128:129]
	ds_read_b128 v[180:183], v149 offset:32768
	ds_read_b128 v[188:191], v149 offset:33792
	ds_read_b128 v[192:195], v149 offset:34816
	ds_read_b128 v[196:199], v149 offset:35840
	ds_read_b128 v[200:203], v149 offset:36864
	ds_read_b128 v[204:207], v149 offset:37888
	ds_read_b128 v[208:211], v149 offset:38912
	ds_read_b128 v[212:215], v149 offset:39936
	global_load_lds_dwordx4 v[224:225], off
	v_lshl_add_u64 v[224:225], s[30:31], 0, v[130:131]
	s_mov_b32 m0, s42
	s_nop 0
	global_load_lds_dwordx4 v[224:225], off
	s_waitcnt vmcnt(8)
	s_waitcnt lgkmcnt(0)
	s_barrier
	s_setprio 1
	s_waitcnt lgkmcnt(0)
	v_mfma_f32_16x16x32_bf16 v[124:127], v[140:143], v[180:183], v[124:127]
	v_mfma_f32_16x16x32_bf16 v[120:123], v[156:159], v[180:183], v[120:123]
	v_mfma_f32_16x16x32_bf16 v[108:111], v[140:143], v[192:195], v[108:111]
	v_mfma_f32_16x16x32_bf16 v[104:107], v[156:159], v[192:195], v[104:107]
	v_mfma_f32_16x16x32_bf16 v[92:95], v[140:143], v[200:203], v[92:95]
	v_mfma_f32_16x16x32_bf16 v[88:91], v[156:159], v[200:203], v[88:91]
	v_mfma_f32_16x16x32_bf16 v[76:79], v[140:143], v[208:211], v[76:79]
	v_mfma_f32_16x16x32_bf16 v[72:75], v[156:159], v[208:211], v[72:75]
	v_mfma_f32_16x16x32_bf16 v[124:127], v[152:155], v[188:191], v[124:127]
	v_mfma_f32_16x16x32_bf16 v[120:123], v[160:163], v[188:191], v[120:123]
	v_mfma_f32_16x16x32_bf16 v[108:111], v[152:155], v[196:199], v[108:111]
	v_mfma_f32_16x16x32_bf16 v[104:107], v[160:163], v[196:199], v[104:107]
	v_mfma_f32_16x16x32_bf16 v[92:95], v[152:155], v[204:207], v[92:95]
	v_mfma_f32_16x16x32_bf16 v[88:91], v[160:163], v[204:207], v[88:91]
	v_mfma_f32_16x16x32_bf16 v[76:79], v[152:155], v[212:215], v[76:79]
	v_mfma_f32_16x16x32_bf16 v[72:75], v[160:163], v[212:215], v[72:75]
	s_setprio 0
	s_setprio 1
	v_mfma_f32_16x16x32_bf16 v[116:119], v[164:167], v[180:183], v[116:119]
	v_mfma_f32_16x16x32_bf16 v[112:115], v[172:175], v[180:183], v[112:115]
	v_mfma_f32_16x16x32_bf16 v[100:103], v[164:167], v[192:195], v[100:103]
	v_mfma_f32_16x16x32_bf16 v[96:99], v[172:175], v[192:195], v[96:99]
	v_mfma_f32_16x16x32_bf16 v[84:87], v[164:167], v[200:203], v[84:87]
	v_mfma_f32_16x16x32_bf16 v[80:83], v[172:175], v[200:203], v[80:83]
	v_mfma_f32_16x16x32_bf16 v[68:71], v[164:167], v[208:211], v[68:71]
	v_mfma_f32_16x16x32_bf16 v[64:67], v[172:175], v[208:211], v[64:67]
	v_mfma_f32_16x16x32_bf16 v[116:119], v[168:171], v[188:191], v[116:119]
	v_mfma_f32_16x16x32_bf16 v[112:115], v[176:179], v[188:191], v[112:115]
	v_mfma_f32_16x16x32_bf16 v[100:103], v[168:171], v[196:199], v[100:103]
	v_mfma_f32_16x16x32_bf16 v[96:99], v[176:179], v[196:199], v[96:99]
	v_mfma_f32_16x16x32_bf16 v[84:87], v[168:171], v[204:207], v[84:87]
	v_mfma_f32_16x16x32_bf16 v[80:83], v[176:179], v[204:207], v[80:83]
	v_mfma_f32_16x16x32_bf16 v[68:71], v[168:171], v[212:215], v[68:71]
	v_mfma_f32_16x16x32_bf16 v[64:67], v[176:179], v[212:215], v[64:67]
	s_setprio 0
	s_barrier
	s_add_i32 s30, s56, s39
	v_lshl_add_u64 v[216:217], v[216:217], 0, s[8:9]
	s_mov_b32 m0, s30
	ds_read_b128 v[180:183], v149 offset:49152
	ds_read_b128 v[188:191], v149 offset:50176
	ds_read_b128 v[192:195], v149 offset:51200
	ds_read_b128 v[196:199], v149 offset:52224
	ds_read_b128 v[200:203], v149 offset:53248
	ds_read_b128 v[204:207], v149 offset:54272
	ds_read_b128 v[208:211], v149 offset:55296
	ds_read_b128 v[212:215], v149 offset:56320
	global_load_lds_dwordx4 v[216:217], off
	s_add_i32 m0, s30, 0x2000
	s_add_u32 s28, s28, 0x40080
	v_lshl_add_u64 v[216:217], v[218:219], 0, s[8:9]
	s_addc_u32 s29, s29, 0
	s_add_i32 s30, s57, s39
	global_load_lds_dwordx4 v[216:217], off
	v_lshl_add_u64 v[216:217], s[28:29], 0, v[128:129]
	s_mov_b32 m0, s30
	s_nop 0
	global_load_lds_dwordx4 v[216:217], off
	v_lshl_add_u64 v[216:217], s[28:29], 0, v[130:131]
	s_add_i32 m0, s30, 0x2000
	s_nop 0
	global_load_lds_dwordx4 v[216:217], off
	v_lshl_add_u64 v[216:217], v[220:221], 0, s[8:9]
	s_mov_b32 m0, s44
	s_nop 0
	global_load_lds_dwordx4 v[216:217], off
	v_lshl_add_u64 v[216:217], v[222:223], 0, s[8:9]
	s_mov_b32 m0, s45
	s_nop 0
	global_load_lds_dwordx4 v[216:217], off
	s_waitcnt vmcnt(8)
	s_waitcnt lgkmcnt(0)
	s_barrier
	s_setprio 1
	s_waitcnt lgkmcnt(0)
	v_mfma_f32_16x16x32_bf16 v[60:63], v[140:143], v[180:183], v[60:63]
	v_mfma_f32_16x16x32_bf16 v[56:59], v[156:159], v[180:183], v[56:59]
	v_mfma_f32_16x16x32_bf16 v[44:47], v[140:143], v[192:195], v[44:47]
	v_mfma_f32_16x16x32_bf16 v[40:43], v[156:159], v[192:195], v[40:43]
	v_mfma_f32_16x16x32_bf16 v[28:31], v[140:143], v[200:203], v[28:31]
	v_mfma_f32_16x16x32_bf16 v[24:27], v[156:159], v[200:203], v[24:27]
	v_mfma_f32_16x16x32_bf16 v[12:15], v[140:143], v[208:211], v[12:15]
	v_mfma_f32_16x16x32_bf16 v[8:11], v[156:159], v[208:211], v[8:11]
	v_mfma_f32_16x16x32_bf16 v[60:63], v[152:155], v[188:191], v[60:63]
	v_mfma_f32_16x16x32_bf16 v[56:59], v[160:163], v[188:191], v[56:59]
	v_mfma_f32_16x16x32_bf16 v[44:47], v[152:155], v[196:199], v[44:47]
	v_mfma_f32_16x16x32_bf16 v[40:43], v[160:163], v[196:199], v[40:43]
	v_mfma_f32_16x16x32_bf16 v[28:31], v[152:155], v[204:207], v[28:31]
	v_mfma_f32_16x16x32_bf16 v[24:27], v[160:163], v[204:207], v[24:27]
	v_mfma_f32_16x16x32_bf16 v[12:15], v[152:155], v[212:215], v[12:15]
	v_mfma_f32_16x16x32_bf16 v[8:11], v[160:163], v[212:215], v[8:11]
	s_setprio 0
	s_setprio 1
	v_mfma_f32_16x16x32_bf16 v[52:55], v[164:167], v[180:183], v[52:55]
	v_mfma_f32_16x16x32_bf16 v[48:51], v[172:175], v[180:183], v[48:51]
	v_mfma_f32_16x16x32_bf16 v[36:39], v[164:167], v[192:195], v[36:39]
	v_mfma_f32_16x16x32_bf16 v[32:35], v[172:175], v[192:195], v[32:35]
	v_mfma_f32_16x16x32_bf16 v[20:23], v[164:167], v[200:203], v[20:23]
	v_mfma_f32_16x16x32_bf16 v[16:19], v[172:175], v[200:203], v[16:19]
	v_mfma_f32_16x16x32_bf16 v[4:7], v[164:167], v[208:211], v[4:7]
	v_mfma_f32_16x16x32_bf16 v[0:3], v[172:175], v[208:211], v[0:3]
	v_mfma_f32_16x16x32_bf16 v[52:55], v[168:171], v[188:191], v[52:55]
	v_mfma_f32_16x16x32_bf16 v[48:51], v[176:179], v[188:191], v[48:51]
	v_mfma_f32_16x16x32_bf16 v[36:39], v[168:171], v[196:199], v[36:39]
	v_mfma_f32_16x16x32_bf16 v[32:35], v[176:179], v[196:199], v[32:35]
	v_mfma_f32_16x16x32_bf16 v[20:23], v[168:171], v[204:207], v[20:23]
	v_mfma_f32_16x16x32_bf16 v[16:19], v[176:179], v[204:207], v[16:19]
	v_mfma_f32_16x16x32_bf16 v[4:7], v[168:171], v[212:215], v[4:7]
	v_mfma_f32_16x16x32_bf16 v[0:3], v[176:179], v[212:215], v[0:3]
	s_setprio 0
	s_add_i32 s55, s55, 2
	s_add_u32 s26, s26, 0x100
	s_addc_u32 s27, s27, 0
	s_add_u32 s53, s53, 0x100
	s_addc_u32 s54, s54, 0
	s_cmp_gt_u32 s55, 13
	s_barrier
	s_cbranch_scc0 .LBB0_427
	s_and_b64 vcc, exec, s[10:11]
	s_cbranch_vccz .LBB0_430
	s_barrier

.LBB0_480:
	ds_read_b128 v[128:131], v183
	ds_read_b128 v[132:135], v183 offset:1024
	ds_read_b128 v[136:139], v183 offset:2048
	ds_read_b128 v[140:143], v183 offset:3072
	ds_read_b128 v[144:147], v187
	ds_read_b128 v[148:151], v187 offset:1024
	ds_read_b128 v[152:155], v187 offset:2048
	ds_read_b128 v[156:159], v187 offset:3072
	s_add_u32 s28, s26, 0xfffc0080
	s_addc_u32 s29, s27, -1
	s_cmp_eq_u32 s55, 12
	s_cselect_b32 s31, s19, s29
	s_cselect_b32 s30, s51, s28
	s_cselect_b32 s29, s17, s54
	s_cselect_b32 s28, s52, s53
	v_lshl_add_u64 v[218:219], s[26:27], 0, v[168:169]
	s_add_i32 m0, s25, 0xc000
	ds_read_b128 v[176:179], v188
	ds_read_b128 v[190:193], v188 offset:1024
	ds_read_b128 v[194:197], v188 offset:2048
	ds_read_b128 v[198:201], v188 offset:3072
	ds_read_b128 v[202:205], v188 offset:4096
	ds_read_b128 v[206:209], v188 offset:5120
	ds_read_b128 v[210:213], v188 offset:6144
	ds_read_b128 v[214:217], v188 offset:7168
	global_load_lds_dwordx4 v[218:219], off
	v_lshl_add_u64 v[218:219], s[26:27], 0, v[170:171]
	s_add_i32 m0, s25, 0xe000
	s_nop 0
	global_load_lds_dwordx4 v[218:219], off
	s_waitcnt vmcnt(8)
	s_waitcnt lgkmcnt(0)
	s_barrier
	s_setprio 1
	s_waitcnt lgkmcnt(0)
	v_mfma_f32_16x16x32_bf16 v[124:127], v[128:131], v[176:179], v[124:127]
	v_mfma_f32_16x16x32_bf16 v[120:123], v[136:139], v[176:179], v[120:123]
	v_mfma_f32_16x16x32_bf16 v[108:111], v[128:131], v[194:197], v[108:111]
	v_mfma_f32_16x16x32_bf16 v[104:107], v[136:139], v[194:197], v[104:107]
	v_mfma_f32_16x16x32_bf16 v[92:95], v[128:131], v[202:205], v[92:95]
	v_mfma_f32_16x16x32_bf16 v[88:91], v[136:139], v[202:205], v[88:91]
	v_mfma_f32_16x16x32_bf16 v[76:79], v[128:131], v[210:213], v[76:79]
	v_mfma_f32_16x16x32_bf16 v[72:75], v[136:139], v[210:213], v[72:75]
	v_mfma_f32_16x16x32_bf16 v[124:127], v[132:135], v[190:193], v[124:127]
	v_mfma_f32_16x16x32_bf16 v[120:123], v[140:143], v[190:193], v[120:123]
	v_mfma_f32_16x16x32_bf16 v[108:111], v[132:135], v[198:201], v[108:111]
	v_mfma_f32_16x16x32_bf16 v[104:107], v[140:143], v[198:201], v[104:107]
	v_mfma_f32_16x16x32_bf16 v[92:95], v[132:135], v[206:209], v[92:95]
	v_mfma_f32_16x16x32_bf16 v[88:91], v[140:143], v[206:209], v[88:91]
	v_mfma_f32_16x16x32_bf16 v[76:79], v[132:135], v[214:217], v[76:79]
	v_mfma_f32_16x16x32_bf16 v[72:75], v[140:143], v[214:217], v[72:75]
	s_setprio 0
	s_setprio 1
	v_mfma_f32_16x16x32_bf16 v[116:119], v[144:147], v[176:179], v[116:119]
	v_mfma_f32_16x16x32_bf16 v[112:115], v[152:155], v[176:179], v[112:115]
	v_mfma_f32_16x16x32_bf16 v[100:103], v[144:147], v[194:197], v[100:103]
	v_mfma_f32_16x16x32_bf16 v[96:99], v[152:155], v[194:197], v[96:99]
	v_mfma_f32_16x16x32_bf16 v[84:87], v[144:147], v[202:205], v[84:87]
	v_mfma_f32_16x16x32_bf16 v[80:83], v[152:155], v[202:205], v[80:83]
	v_mfma_f32_16x16x32_bf16 v[68:71], v[144:147], v[210:213], v[68:71]
	v_mfma_f32_16x16x32_bf16 v[64:67], v[152:155], v[210:213], v[64:67]
	v_mfma_f32_16x16x32_bf16 v[116:119], v[148:151], v[190:193], v[116:119]
	v_mfma_f32_16x16x32_bf16 v[112:115], v[156:159], v[190:193], v[112:115]
	v_mfma_f32_16x16x32_bf16 v[100:103], v[148:151], v[198:201], v[100:103]
	v_mfma_f32_16x16x32_bf16 v[96:99], v[156:159], v[198:201], v[96:99]
	v_mfma_f32_16x16x32_bf16 v[84:87], v[148:151], v[206:209], v[84:87]
	v_mfma_f32_16x16x32_bf16 v[80:83], v[156:159], v[206:209], v[80:83]
	v_mfma_f32_16x16x32_bf16 v[68:71], v[148:151], v[214:217], v[68:71]
	v_mfma_f32_16x16x32_bf16 v[64:67], v[156:159], v[214:217], v[64:67]
	s_setprio 0
	s_barrier
	s_add_i32 s56, s48, s38
	v_lshl_add_u64 v[218:219], s[28:29], 0, v[162:163]
	s_mov_b32 m0, s56
	ds_read_b128 v[176:179], v188 offset:16384
	ds_read_b128 v[190:193], v188 offset:17408
	ds_read_b128 v[194:197], v188 offset:18432
	ds_read_b128 v[198:201], v188 offset:19456
	ds_read_b128 v[202:205], v188 offset:20480
	ds_read_b128 v[206:209], v188 offset:21504
	ds_read_b128 v[210:213], v188 offset:22528
	ds_read_b128 v[214:217], v188 offset:23552
	global_load_lds_dwordx4 v[218:219], off
	s_add_i32 m0, s56, 0x2000
	s_add_u32 s56, s28, 0x40000
	v_lshl_add_u64 v[220:221], s[28:29], 0, v[166:167]
	s_addc_u32 s57, s29, 0
	s_add_i32 s60, s49, s38
	global_load_lds_dwordx4 v[220:221], off
	v_lshl_add_u64 v[222:223], s[56:57], 0, v[162:163]
	s_mov_b32 m0, s60
	v_lshl_add_u64 v[224:225], s[30:31], 0, v[164:165]
	global_load_lds_dwordx4 v[222:223], off
	v_lshl_add_u64 v[222:223], s[56:57], 0, v[166:167]
	s_add_i32 m0, s60, 0x2000
	s_nop 0
	global_load_lds_dwordx4 v[222:223], off
	v_lshl_add_u64 v[222:223], s[30:31], 0, v[160:161]
	s_mov_b32 m0, s25
	s_nop 0
	global_load_lds_dwordx4 v[222:223], off
	s_mov_b32 m0, s39
	s_nop 0
	global_load_lds_dwordx4 v[224:225], off
	s_waitcnt vmcnt(8)
	s_waitcnt lgkmcnt(0)
	s_barrier
	s_setprio 1
	s_waitcnt lgkmcnt(0)
	v_mfma_f32_16x16x32_bf16 v[60:63], v[128:131], v[176:179], v[60:63]
	v_mfma_f32_16x16x32_bf16 v[56:59], v[136:139], v[176:179], v[56:59]
	v_mfma_f32_16x16x32_bf16 v[44:47], v[128:131], v[194:197], v[44:47]
	v_mfma_f32_16x16x32_bf16 v[40:43], v[136:139], v[194:197], v[40:43]
	v_mfma_f32_16x16x32_bf16 v[28:31], v[128:131], v[202:205], v[28:31]
	v_mfma_f32_16x16x32_bf16 v[24:27], v[136:139], v[202:205], v[24:27]
	v_mfma_f32_16x16x32_bf16 v[12:15], v[128:131], v[210:213], v[12:15]
	v_mfma_f32_16x16x32_bf16 v[8:11], v[136:139], v[210:213], v[8:11]
	v_mfma_f32_16x16x32_bf16 v[60:63], v[132:135], v[190:193], v[60:63]
	v_mfma_f32_16x16x32_bf16 v[56:59], v[140:143], v[190:193], v[56:59]
	v_mfma_f32_16x16x32_bf16 v[44:47], v[132:135], v[198:201], v[44:47]
	v_mfma_f32_16x16x32_bf16 v[40:43], v[140:143], v[198:201], v[40:43]
	v_mfma_f32_16x16x32_bf16 v[28:31], v[132:135], v[206:209], v[28:31]
	v_mfma_f32_16x16x32_bf16 v[24:27], v[140:143], v[206:209], v[24:27]
	v_mfma_f32_16x16x32_bf16 v[12:15], v[132:135], v[214:217], v[12:15]
	v_mfma_f32_16x16x32_bf16 v[8:11], v[140:143], v[214:217], v[8:11]
	s_setprio 0
	s_setprio 1
	v_mfma_f32_16x16x32_bf16 v[52:55], v[144:147], v[176:179], v[52:55]
	v_mfma_f32_16x16x32_bf16 v[48:51], v[152:155], v[176:179], v[48:51]
	v_mfma_f32_16x16x32_bf16 v[36:39], v[144:147], v[194:197], v[36:39]
	v_mfma_f32_16x16x32_bf16 v[32:35], v[152:155], v[194:197], v[32:35]
	v_mfma_f32_16x16x32_bf16 v[20:23], v[144:147], v[202:205], v[20:23]
	v_mfma_f32_16x16x32_bf16 v[16:19], v[152:155], v[202:205], v[16:19]
	v_mfma_f32_16x16x32_bf16 v[4:7], v[144:147], v[210:213], v[4:7]
	v_mfma_f32_16x16x32_bf16 v[0:3], v[152:155], v[210:213], v[0:3]
	v_mfma_f32_16x16x32_bf16 v[52:55], v[148:151], v[190:193], v[52:55]
	v_mfma_f32_16x16x32_bf16 v[48:51], v[156:159], v[190:193], v[48:51]
	v_mfma_f32_16x16x32_bf16 v[36:39], v[148:151], v[198:201], v[36:39]
	v_mfma_f32_16x16x32_bf16 v[32:35], v[156:159], v[198:201], v[32:35]
	v_mfma_f32_16x16x32_bf16 v[20:23], v[148:151], v[206:209], v[20:23]
	v_mfma_f32_16x16x32_bf16 v[16:19], v[156:159], v[206:209], v[16:19]
	v_mfma_f32_16x16x32_bf16 v[4:7], v[148:151], v[214:217], v[4:7]
	v_mfma_f32_16x16x32_bf16 v[0:3], v[156:159], v[214:217], v[0:3]
	s_setprio 0
	s_barrier
	s_add_i32 s56, 0, 0x18000
	s_add_i32 s57, 0, 0x1c000
	v_add_u32_e32 v140, s56, v181
	v_add_u32_e32 v156, s57, v181
	ds_read_b128 v[128:131], v140
	ds_read_b128 v[132:135], v140 offset:1024
	ds_read_b128 v[136:139], v140 offset:2048
	ds_read_b128 v[140:143], v140 offset:3072
	ds_read_b128 v[144:147], v156
	ds_read_b128 v[148:151], v156 offset:1024
	ds_read_b128 v[152:155], v156 offset:2048
	ds_read_b128 v[156:159], v156 offset:3072
	s_add_u32 s30, s30, 0x40000
	s_addc_u32 s31, s31, 0
	s_mov_b32 m0, s40
	v_lshl_add_u64 v[226:227], s[30:31], 0, v[160:161]
	ds_read_b128 v[176:179], v188 offset:32768
	ds_read_b128 v[190:193], v188 offset:33792
	ds_read_b128 v[194:197], v188 offset:34816
	ds_read_b128 v[198:201], v188 offset:35840
	ds_read_b128 v[202:205], v188 offset:36864
	ds_read_b128 v[206:209], v188 offset:37888
	ds_read_b128 v[210:213], v188 offset:38912
	ds_read_b128 v[214:217], v188 offset:39936
	global_load_lds_dwordx4 v[226:227], off
	v_lshl_add_u64 v[226:227], s[30:31], 0, v[164:165]
	s_mov_b32 m0, s41
	s_nop 0
	global_load_lds_dwordx4 v[226:227], off
	s_waitcnt vmcnt(8)
	s_waitcnt lgkmcnt(0)
	s_barrier
	s_setprio 1
	s_waitcnt lgkmcnt(0)
	v_mfma_f32_16x16x32_bf16 v[124:127], v[128:131], v[176:179], v[124:127]
	v_mfma_f32_16x16x32_bf16 v[120:123], v[136:139], v[176:179], v[120:123]
	v_mfma_f32_16x16x32_bf16 v[108:111], v[128:131], v[194:197], v[108:111]
	v_mfma_f32_16x16x32_bf16 v[104:107], v[136:139], v[194:197], v[104:107]
	v_mfma_f32_16x16x32_bf16 v[92:95], v[128:131], v[202:205], v[92:95]
	v_mfma_f32_16x16x32_bf16 v[88:91], v[136:139], v[202:205], v[88:91]
	v_mfma_f32_16x16x32_bf16 v[76:79], v[128:131], v[210:213], v[76:79]
	v_mfma_f32_16x16x32_bf16 v[72:75], v[136:139], v[210:213], v[72:75]
	v_mfma_f32_16x16x32_bf16 v[124:127], v[132:135], v[190:193], v[124:127]
	v_mfma_f32_16x16x32_bf16 v[120:123], v[140:143], v[190:193], v[120:123]
	v_mfma_f32_16x16x32_bf16 v[108:111], v[132:135], v[198:201], v[108:111]
	v_mfma_f32_16x16x32_bf16 v[104:107], v[140:143], v[198:201], v[104:107]
	v_mfma_f32_16x16x32_bf16 v[92:95], v[132:135], v[206:209], v[92:95]
	v_mfma_f32_16x16x32_bf16 v[88:91], v[140:143], v[206:209], v[88:91]
	v_mfma_f32_16x16x32_bf16 v[76:79], v[132:135], v[214:217], v[76:79]
	v_mfma_f32_16x16x32_bf16 v[72:75], v[140:143], v[214:217], v[72:75]
	s_setprio 0
	s_setprio 1
	v_mfma_f32_16x16x32_bf16 v[116:119], v[144:147], v[176:179], v[116:119]
	v_mfma_f32_16x16x32_bf16 v[112:115], v[152:155], v[176:179], v[112:115]
	v_mfma_f32_16x16x32_bf16 v[100:103], v[144:147], v[194:197], v[100:103]
	v_mfma_f32_16x16x32_bf16 v[96:99], v[152:155], v[194:197], v[96:99]
	v_mfma_f32_16x16x32_bf16 v[84:87], v[144:147], v[202:205], v[84:87]
	v_mfma_f32_16x16x32_bf16 v[80:83], v[152:155], v[202:205], v[80:83]
	v_mfma_f32_16x16x32_bf16 v[68:71], v[144:147], v[210:213], v[68:71]
	v_mfma_f32_16x16x32_bf16 v[64:67], v[152:155], v[210:213], v[64:67]
	v_mfma_f32_16x16x32_bf16 v[116:119], v[148:151], v[190:193], v[116:119]
	v_mfma_f32_16x16x32_bf16 v[112:115], v[156:159], v[190:193], v[112:115]
	v_mfma_f32_16x16x32_bf16 v[100:103], v[148:151], v[198:201], v[100:103]
	v_mfma_f32_16x16x32_bf16 v[96:99], v[156:159], v[198:201], v[96:99]
	v_mfma_f32_16x16x32_bf16 v[84:87], v[148:151], v[206:209], v[84:87]
	v_mfma_f32_16x16x32_bf16 v[80:83], v[156:159], v[206:209], v[80:83]
	v_mfma_f32_16x16x32_bf16 v[68:71], v[148:151], v[214:217], v[68:71]
	v_mfma_f32_16x16x32_bf16 v[64:67], v[156:159], v[214:217], v[64:67]
	s_setprio 0
	s_barrier
	s_add_i32 s30, s56, s38
	v_lshl_add_u64 v[218:219], v[218:219], 0, s[10:11]
	s_mov_b32 m0, s30
	ds_read_b128 v[176:179], v188 offset:49152
	ds_read_b128 v[190:193], v188 offset:50176
	ds_read_b128 v[194:197], v188 offset:51200
	ds_read_b128 v[198:201], v188 offset:52224
	ds_read_b128 v[202:205], v188 offset:53248
	ds_read_b128 v[206:209], v188 offset:54272
	ds_read_b128 v[210:213], v188 offset:55296
	ds_read_b128 v[214:217], v188 offset:56320
	global_load_lds_dwordx4 v[218:219], off
	s_add_i32 m0, s30, 0x2000
	s_add_u32 s28, s28, 0x40080
	v_lshl_add_u64 v[218:219], v[220:221], 0, s[10:11]
	s_addc_u32 s29, s29, 0
	s_add_i32 s30, s57, s38
	global_load_lds_dwordx4 v[218:219], off
	v_lshl_add_u64 v[218:219], s[28:29], 0, v[162:163]
	s_mov_b32 m0, s30
	s_nop 0
	global_load_lds_dwordx4 v[218:219], off
	v_lshl_add_u64 v[218:219], s[28:29], 0, v[166:167]
	s_add_i32 m0, s30, 0x2000
	s_nop 0
	global_load_lds_dwordx4 v[218:219], off
	v_lshl_add_u64 v[218:219], v[222:223], 0, s[10:11]
	s_mov_b32 m0, s43
	s_nop 0
	global_load_lds_dwordx4 v[218:219], off
	v_lshl_add_u64 v[218:219], v[224:225], 0, s[10:11]
	s_mov_b32 m0, s44
	s_nop 0
	global_load_lds_dwordx4 v[218:219], off
	s_waitcnt vmcnt(8)
	s_waitcnt lgkmcnt(0)
	s_barrier
	s_setprio 1
	s_waitcnt lgkmcnt(0)
	v_mfma_f32_16x16x32_bf16 v[60:63], v[128:131], v[176:179], v[60:63]
	v_mfma_f32_16x16x32_bf16 v[56:59], v[136:139], v[176:179], v[56:59]
	v_mfma_f32_16x16x32_bf16 v[44:47], v[128:131], v[194:197], v[44:47]
	v_mfma_f32_16x16x32_bf16 v[40:43], v[136:139], v[194:197], v[40:43]
	v_mfma_f32_16x16x32_bf16 v[28:31], v[128:131], v[202:205], v[28:31]
	v_mfma_f32_16x16x32_bf16 v[24:27], v[136:139], v[202:205], v[24:27]
	v_mfma_f32_16x16x32_bf16 v[12:15], v[128:131], v[210:213], v[12:15]
	v_mfma_f32_16x16x32_bf16 v[8:11], v[136:139], v[210:213], v[8:11]
	v_mfma_f32_16x16x32_bf16 v[60:63], v[132:135], v[190:193], v[60:63]
	v_mfma_f32_16x16x32_bf16 v[56:59], v[140:143], v[190:193], v[56:59]
	v_mfma_f32_16x16x32_bf16 v[44:47], v[132:135], v[198:201], v[44:47]
	v_mfma_f32_16x16x32_bf16 v[40:43], v[140:143], v[198:201], v[40:43]
	v_mfma_f32_16x16x32_bf16 v[28:31], v[132:135], v[206:209], v[28:31]
	v_mfma_f32_16x16x32_bf16 v[24:27], v[140:143], v[206:209], v[24:27]
	v_mfma_f32_16x16x32_bf16 v[12:15], v[132:135], v[214:217], v[12:15]
	v_mfma_f32_16x16x32_bf16 v[8:11], v[140:143], v[214:217], v[8:11]
	s_setprio 0
	s_setprio 1
	v_mfma_f32_16x16x32_bf16 v[52:55], v[144:147], v[176:179], v[52:55]
	v_mfma_f32_16x16x32_bf16 v[48:51], v[152:155], v[176:179], v[48:51]
	v_mfma_f32_16x16x32_bf16 v[36:39], v[144:147], v[194:197], v[36:39]
	v_mfma_f32_16x16x32_bf16 v[32:35], v[152:155], v[194:197], v[32:35]
	v_mfma_f32_16x16x32_bf16 v[20:23], v[144:147], v[202:205], v[20:23]
	v_mfma_f32_16x16x32_bf16 v[16:19], v[152:155], v[202:205], v[16:19]
	v_mfma_f32_16x16x32_bf16 v[4:7], v[144:147], v[210:213], v[4:7]
	v_mfma_f32_16x16x32_bf16 v[0:3], v[152:155], v[210:213], v[0:3]
	v_mfma_f32_16x16x32_bf16 v[52:55], v[148:151], v[190:193], v[52:55]
	v_mfma_f32_16x16x32_bf16 v[48:51], v[156:159], v[190:193], v[48:51]
	v_mfma_f32_16x16x32_bf16 v[36:39], v[148:151], v[198:201], v[36:39]
	v_mfma_f32_16x16x32_bf16 v[32:35], v[156:159], v[198:201], v[32:35]
	v_mfma_f32_16x16x32_bf16 v[20:23], v[148:151], v[206:209], v[20:23]
	v_mfma_f32_16x16x32_bf16 v[16:19], v[156:159], v[206:209], v[16:19]
	v_mfma_f32_16x16x32_bf16 v[4:7], v[148:151], v[214:217], v[4:7]
	v_mfma_f32_16x16x32_bf16 v[0:3], v[156:159], v[214:217], v[0:3]
	s_setprio 0
	s_add_i32 s55, s55, 2
	s_add_u32 s26, s26, 0x100
	s_addc_u32 s27, s27, 0
	s_add_u32 s53, s53, 0x100
	s_addc_u32 s54, s54, 0
	s_cmp_gt_u32 s55, 13
	s_barrier
	s_cbranch_scc0 .LBB0_480
	s_and_b64 vcc, exec, s[12:13]
	s_cbranch_vccz .LBB0_483
	s_barrier

.LBB0_535:
	ds_read_b128 v[80:83], v192
	ds_read_b128 v[84:87], v192 offset:1024
	ds_read_b128 v[88:91], v192 offset:2048
	ds_read_b128 v[92:95], v192 offset:3072
	ds_read_b128 v[96:99], v193
	ds_read_b128 v[100:103], v193 offset:1024
	ds_read_b128 v[104:107], v193 offset:2048
	ds_read_b128 v[108:111], v193 offset:3072
	s_add_u32 s26, s24, 0xfffc0080
	s_addc_u32 s27, s25, -1
	s_cmp_eq_u32 s50, 12
	s_cselect_b32 s29, s17, s27
	s_cselect_b32 s28, s44, s26
	s_cselect_b32 s27, s15, s49
	s_cselect_b32 s26, s45, s48
	v_lshl_add_u64 v[188:189], s[24:25], 0, v[164:165]
	s_add_i32 m0, s23, 0xc000
	ds_read_b128 v[172:175], v194
	ds_read_b128 v[176:179], v194 offset:1024
	ds_read_b128 v[180:183], v194 offset:2048
	ds_read_b128 v[196:199], v194 offset:3072
	ds_read_b128 v[200:203], v194 offset:4096
	ds_read_b128 v[204:207], v194 offset:5120
	ds_read_b128 v[208:211], v194 offset:6144
	ds_read_b128 v[212:215], v194 offset:7168
	global_load_lds_dwordx4 v[188:189], off
	v_lshl_add_u64 v[188:189], s[24:25], 0, v[166:167]
	s_add_i32 m0, s23, 0xe000
	s_nop 0
	global_load_lds_dwordx4 v[188:189], off
	s_waitcnt vmcnt(8)
	s_waitcnt lgkmcnt(0)
	s_barrier
	s_setprio 1
	s_waitcnt lgkmcnt(0)
	v_mfma_f32_16x16x32_bf16 v[156:159], v[80:83], v[172:175], v[156:159]
	v_mfma_f32_16x16x32_bf16 v[152:155], v[88:91], v[172:175], v[152:155]
	v_mfma_f32_16x16x32_bf16 v[140:143], v[80:83], v[180:183], v[140:143]
	v_mfma_f32_16x16x32_bf16 v[136:139], v[88:91], v[180:183], v[136:139]
	v_mfma_f32_16x16x32_bf16 v[124:127], v[80:83], v[200:203], v[124:127]
	v_mfma_f32_16x16x32_bf16 v[120:123], v[88:91], v[200:203], v[120:123]
	v_mfma_f32_16x16x32_bf16 v[76:79], v[80:83], v[208:211], v[76:79]
	v_mfma_f32_16x16x32_bf16 v[72:75], v[88:91], v[208:211], v[72:75]
	v_mfma_f32_16x16x32_bf16 v[156:159], v[84:87], v[176:179], v[156:159]
	v_mfma_f32_16x16x32_bf16 v[152:155], v[92:95], v[176:179], v[152:155]
	v_mfma_f32_16x16x32_bf16 v[140:143], v[84:87], v[196:199], v[140:143]
	v_mfma_f32_16x16x32_bf16 v[136:139], v[92:95], v[196:199], v[136:139]
	v_mfma_f32_16x16x32_bf16 v[124:127], v[84:87], v[204:207], v[124:127]
	v_mfma_f32_16x16x32_bf16 v[120:123], v[92:95], v[204:207], v[120:123]
	v_mfma_f32_16x16x32_bf16 v[76:79], v[84:87], v[212:215], v[76:79]
	v_mfma_f32_16x16x32_bf16 v[72:75], v[92:95], v[212:215], v[72:75]
	s_setprio 0
	s_setprio 1
	v_mfma_f32_16x16x32_bf16 v[148:151], v[96:99], v[172:175], v[148:151]
	v_mfma_f32_16x16x32_bf16 v[144:147], v[104:107], v[172:175], v[144:147]
	v_mfma_f32_16x16x32_bf16 v[132:135], v[96:99], v[180:183], v[132:135]
	v_mfma_f32_16x16x32_bf16 v[128:131], v[104:107], v[180:183], v[128:131]
	v_mfma_f32_16x16x32_bf16 v[116:119], v[96:99], v[200:203], v[116:119]
	v_mfma_f32_16x16x32_bf16 v[112:115], v[104:107], v[200:203], v[112:115]
	v_mfma_f32_16x16x32_bf16 v[68:71], v[96:99], v[208:211], v[68:71]
	v_mfma_f32_16x16x32_bf16 v[64:67], v[104:107], v[208:211], v[64:67]
	v_mfma_f32_16x16x32_bf16 v[148:151], v[100:103], v[176:179], v[148:151]
	v_mfma_f32_16x16x32_bf16 v[144:147], v[108:111], v[176:179], v[144:147]
	v_mfma_f32_16x16x32_bf16 v[132:135], v[100:103], v[196:199], v[132:135]
	v_mfma_f32_16x16x32_bf16 v[128:131], v[108:111], v[196:199], v[128:131]
	v_mfma_f32_16x16x32_bf16 v[116:119], v[100:103], v[204:207], v[116:119]
	v_mfma_f32_16x16x32_bf16 v[112:115], v[108:111], v[204:207], v[112:115]
	v_mfma_f32_16x16x32_bf16 v[68:71], v[100:103], v[212:215], v[68:71]
	v_mfma_f32_16x16x32_bf16 v[64:67], v[108:111], v[212:215], v[64:67]
	s_setprio 0
	s_barrier
	s_add_i32 s51, s41, s31
	v_lshl_add_u64 v[188:189], s[26:27], 0, v[160:161]
	s_mov_b32 m0, s51
	ds_read_b128 v[172:175], v194 offset:16384
	ds_read_b128 v[176:179], v194 offset:17408
	ds_read_b128 v[180:183], v194 offset:18432
	ds_read_b128 v[196:199], v194 offset:19456
	ds_read_b128 v[200:203], v194 offset:20480
	ds_read_b128 v[204:207], v194 offset:21504
	ds_read_b128 v[208:211], v194 offset:22528
	ds_read_b128 v[212:215], v194 offset:23552
	global_load_lds_dwordx4 v[188:189], off
	s_add_i32 m0, s51, 0x2000
	s_add_u32 s52, s26, 0x40000
	v_lshl_add_u64 v[216:217], s[26:27], 0, v[162:163]
	s_addc_u32 s53, s27, 0
	s_add_i32 s51, s42, s31
	global_load_lds_dwordx4 v[216:217], off
	v_lshl_add_u64 v[218:219], s[52:53], 0, v[160:161]
	s_mov_b32 m0, s51
	v_lshl_add_u64 v[220:221], s[28:29], 0, v[162:163]
	global_load_lds_dwordx4 v[218:219], off
	v_lshl_add_u64 v[218:219], s[52:53], 0, v[162:163]
	s_add_i32 m0, s51, 0x2000
	s_nop 0
	global_load_lds_dwordx4 v[218:219], off
	v_lshl_add_u64 v[218:219], s[28:29], 0, v[160:161]
	s_mov_b32 m0, s23
	s_nop 0
	global_load_lds_dwordx4 v[218:219], off
	s_mov_b32 m0, s34
	s_nop 0
	global_load_lds_dwordx4 v[220:221], off
	s_waitcnt vmcnt(8)
	s_waitcnt lgkmcnt(0)
	s_barrier
	s_setprio 1
	s_waitcnt lgkmcnt(0)
	v_mfma_f32_16x16x32_bf16 v[60:63], v[80:83], v[172:175], v[60:63]
	v_mfma_f32_16x16x32_bf16 v[56:59], v[88:91], v[172:175], v[56:59]
	v_mfma_f32_16x16x32_bf16 v[44:47], v[80:83], v[180:183], v[44:47]
	v_mfma_f32_16x16x32_bf16 v[40:43], v[88:91], v[180:183], v[40:43]
	v_mfma_f32_16x16x32_bf16 v[28:31], v[80:83], v[200:203], v[28:31]
	v_mfma_f32_16x16x32_bf16 v[24:27], v[88:91], v[200:203], v[24:27]
	v_mfma_f32_16x16x32_bf16 v[12:15], v[80:83], v[208:211], v[12:15]
	v_mfma_f32_16x16x32_bf16 v[8:11], v[88:91], v[208:211], v[8:11]
	v_mfma_f32_16x16x32_bf16 v[60:63], v[84:87], v[176:179], v[60:63]
	v_mfma_f32_16x16x32_bf16 v[56:59], v[92:95], v[176:179], v[56:59]
	v_mfma_f32_16x16x32_bf16 v[44:47], v[84:87], v[196:199], v[44:47]
	v_mfma_f32_16x16x32_bf16 v[40:43], v[92:95], v[196:199], v[40:43]
	v_mfma_f32_16x16x32_bf16 v[28:31], v[84:87], v[204:207], v[28:31]
	v_mfma_f32_16x16x32_bf16 v[24:27], v[92:95], v[204:207], v[24:27]
	v_mfma_f32_16x16x32_bf16 v[12:15], v[84:87], v[212:215], v[12:15]
	v_mfma_f32_16x16x32_bf16 v[8:11], v[92:95], v[212:215], v[8:11]
	s_setprio 0
	s_setprio 1
	v_mfma_f32_16x16x32_bf16 v[52:55], v[96:99], v[172:175], v[52:55]
	v_mfma_f32_16x16x32_bf16 v[48:51], v[104:107], v[172:175], v[48:51]
	v_mfma_f32_16x16x32_bf16 v[36:39], v[96:99], v[180:183], v[36:39]
	v_mfma_f32_16x16x32_bf16 v[32:35], v[104:107], v[180:183], v[32:35]
	v_mfma_f32_16x16x32_bf16 v[20:23], v[96:99], v[200:203], v[20:23]
	v_mfma_f32_16x16x32_bf16 v[16:19], v[104:107], v[200:203], v[16:19]
	v_mfma_f32_16x16x32_bf16 v[4:7], v[96:99], v[208:211], v[4:7]
	v_mfma_f32_16x16x32_bf16 v[0:3], v[104:107], v[208:211], v[0:3]
	v_mfma_f32_16x16x32_bf16 v[52:55], v[100:103], v[176:179], v[52:55]
	v_mfma_f32_16x16x32_bf16 v[48:51], v[108:111], v[176:179], v[48:51]
	v_mfma_f32_16x16x32_bf16 v[36:39], v[100:103], v[196:199], v[36:39]
	v_mfma_f32_16x16x32_bf16 v[32:35], v[108:111], v[196:199], v[32:35]
	v_mfma_f32_16x16x32_bf16 v[20:23], v[100:103], v[204:207], v[20:23]
	v_mfma_f32_16x16x32_bf16 v[16:19], v[108:111], v[204:207], v[16:19]
	v_mfma_f32_16x16x32_bf16 v[4:7], v[100:103], v[212:215], v[4:7]
	v_mfma_f32_16x16x32_bf16 v[0:3], v[108:111], v[212:215], v[0:3]
	s_setprio 0
	s_barrier
	s_add_i32 s51, 0, 0x18000
	s_add_i32 s52, 0, 0x1c000
	v_add_u32_e32 v92, s51, v190
	v_add_u32_e32 v108, s52, v190
	ds_read_b128 v[80:83], v92
	ds_read_b128 v[84:87], v92 offset:1024
	ds_read_b128 v[88:91], v92 offset:2048
	ds_read_b128 v[92:95], v92 offset:3072
	ds_read_b128 v[96:99], v108
	ds_read_b128 v[100:103], v108 offset:1024
	ds_read_b128 v[104:107], v108 offset:2048
	ds_read_b128 v[108:111], v108 offset:3072
	s_add_u32 s28, s28, 0x40000
	s_addc_u32 s29, s29, 0
	s_mov_b32 m0, s35
	v_lshl_add_u64 v[222:223], s[28:29], 0, v[160:161]
	ds_read_b128 v[172:175], v194 offset:32768
	ds_read_b128 v[176:179], v194 offset:33792
	ds_read_b128 v[180:183], v194 offset:34816
	ds_read_b128 v[196:199], v194 offset:35840
	ds_read_b128 v[200:203], v194 offset:36864
	ds_read_b128 v[204:207], v194 offset:37888
	ds_read_b128 v[208:211], v194 offset:38912
	ds_read_b128 v[212:215], v194 offset:39936
	global_load_lds_dwordx4 v[222:223], off
	v_lshl_add_u64 v[222:223], s[28:29], 0, v[162:163]
	s_mov_b32 m0, s36
	s_nop 0
	global_load_lds_dwordx4 v[222:223], off
	s_waitcnt vmcnt(8)
	s_waitcnt lgkmcnt(0)
	s_barrier
	s_setprio 1
	s_waitcnt lgkmcnt(0)
	v_mfma_f32_16x16x32_bf16 v[156:159], v[80:83], v[172:175], v[156:159]
	v_mfma_f32_16x16x32_bf16 v[152:155], v[88:91], v[172:175], v[152:155]
	v_mfma_f32_16x16x32_bf16 v[140:143], v[80:83], v[180:183], v[140:143]
	v_mfma_f32_16x16x32_bf16 v[136:139], v[88:91], v[180:183], v[136:139]
	v_mfma_f32_16x16x32_bf16 v[124:127], v[80:83], v[200:203], v[124:127]
	v_mfma_f32_16x16x32_bf16 v[120:123], v[88:91], v[200:203], v[120:123]
	v_mfma_f32_16x16x32_bf16 v[76:79], v[80:83], v[208:211], v[76:79]
	v_mfma_f32_16x16x32_bf16 v[72:75], v[88:91], v[208:211], v[72:75]
	v_mfma_f32_16x16x32_bf16 v[156:159], v[84:87], v[176:179], v[156:159]
	v_mfma_f32_16x16x32_bf16 v[152:155], v[92:95], v[176:179], v[152:155]
	v_mfma_f32_16x16x32_bf16 v[140:143], v[84:87], v[196:199], v[140:143]
	v_mfma_f32_16x16x32_bf16 v[136:139], v[92:95], v[196:199], v[136:139]
	v_mfma_f32_16x16x32_bf16 v[124:127], v[84:87], v[204:207], v[124:127]
	v_mfma_f32_16x16x32_bf16 v[120:123], v[92:95], v[204:207], v[120:123]
	v_mfma_f32_16x16x32_bf16 v[76:79], v[84:87], v[212:215], v[76:79]
	v_mfma_f32_16x16x32_bf16 v[72:75], v[92:95], v[212:215], v[72:75]
	s_setprio 0
	s_setprio 1
	v_mfma_f32_16x16x32_bf16 v[148:151], v[96:99], v[172:175], v[148:151]
	v_mfma_f32_16x16x32_bf16 v[144:147], v[104:107], v[172:175], v[144:147]
	v_mfma_f32_16x16x32_bf16 v[132:135], v[96:99], v[180:183], v[132:135]
	v_mfma_f32_16x16x32_bf16 v[128:131], v[104:107], v[180:183], v[128:131]
	v_mfma_f32_16x16x32_bf16 v[116:119], v[96:99], v[200:203], v[116:119]
	v_mfma_f32_16x16x32_bf16 v[112:115], v[104:107], v[200:203], v[112:115]
	v_mfma_f32_16x16x32_bf16 v[68:71], v[96:99], v[208:211], v[68:71]
	v_mfma_f32_16x16x32_bf16 v[64:67], v[104:107], v[208:211], v[64:67]
	v_mfma_f32_16x16x32_bf16 v[148:151], v[100:103], v[176:179], v[148:151]
	v_mfma_f32_16x16x32_bf16 v[144:147], v[108:111], v[176:179], v[144:147]
	v_mfma_f32_16x16x32_bf16 v[132:135], v[100:103], v[196:199], v[132:135]
	v_mfma_f32_16x16x32_bf16 v[128:131], v[108:111], v[196:199], v[128:131]
	v_mfma_f32_16x16x32_bf16 v[116:119], v[100:103], v[204:207], v[116:119]
	v_mfma_f32_16x16x32_bf16 v[112:115], v[108:111], v[204:207], v[112:115]
	v_mfma_f32_16x16x32_bf16 v[68:71], v[100:103], v[212:215], v[68:71]
	v_mfma_f32_16x16x32_bf16 v[64:67], v[108:111], v[212:215], v[64:67]
	s_setprio 0
	s_barrier
	s_add_i32 s28, s51, s31
	v_lshl_add_u64 v[188:189], v[188:189], 0, s[6:7]
	s_mov_b32 m0, s28
	ds_read_b128 v[172:175], v194 offset:49152
	ds_read_b128 v[176:179], v194 offset:50176
	ds_read_b128 v[180:183], v194 offset:51200
	ds_read_b128 v[196:199], v194 offset:52224
	ds_read_b128 v[200:203], v194 offset:53248
	ds_read_b128 v[204:207], v194 offset:54272
	ds_read_b128 v[208:211], v194 offset:55296
	ds_read_b128 v[212:215], v194 offset:56320
	global_load_lds_dwordx4 v[188:189], off
	s_add_i32 m0, s28, 0x2000
	s_add_u32 s26, s26, 0x40080
	v_lshl_add_u64 v[188:189], v[216:217], 0, s[6:7]
	s_addc_u32 s27, s27, 0
	s_add_i32 s28, s52, s31
	global_load_lds_dwordx4 v[188:189], off
	v_lshl_add_u64 v[188:189], s[26:27], 0, v[160:161]
	s_mov_b32 m0, s28
	s_nop 0
	global_load_lds_dwordx4 v[188:189], off
	v_lshl_add_u64 v[188:189], s[26:27], 0, v[162:163]
	s_add_i32 m0, s28, 0x2000
	s_nop 0
	global_load_lds_dwordx4 v[188:189], off
	v_lshl_add_u64 v[188:189], v[218:219], 0, s[6:7]
	s_mov_b32 m0, s38
	s_nop 0
	global_load_lds_dwordx4 v[188:189], off
	v_lshl_add_u64 v[188:189], v[220:221], 0, s[6:7]
	s_mov_b32 m0, s39
	s_nop 0
	global_load_lds_dwordx4 v[188:189], off
	s_waitcnt vmcnt(8)
	s_waitcnt lgkmcnt(0)
	s_barrier
	s_setprio 1
	s_waitcnt lgkmcnt(0)
	v_mfma_f32_16x16x32_bf16 v[60:63], v[80:83], v[172:175], v[60:63]
	v_mfma_f32_16x16x32_bf16 v[56:59], v[88:91], v[172:175], v[56:59]
	v_mfma_f32_16x16x32_bf16 v[44:47], v[80:83], v[180:183], v[44:47]
	v_mfma_f32_16x16x32_bf16 v[40:43], v[88:91], v[180:183], v[40:43]
	v_mfma_f32_16x16x32_bf16 v[28:31], v[80:83], v[200:203], v[28:31]
	v_mfma_f32_16x16x32_bf16 v[24:27], v[88:91], v[200:203], v[24:27]
	v_mfma_f32_16x16x32_bf16 v[12:15], v[80:83], v[208:211], v[12:15]
	v_mfma_f32_16x16x32_bf16 v[8:11], v[88:91], v[208:211], v[8:11]
	v_mfma_f32_16x16x32_bf16 v[60:63], v[84:87], v[176:179], v[60:63]
	v_mfma_f32_16x16x32_bf16 v[56:59], v[92:95], v[176:179], v[56:59]
	v_mfma_f32_16x16x32_bf16 v[44:47], v[84:87], v[196:199], v[44:47]
	v_mfma_f32_16x16x32_bf16 v[40:43], v[92:95], v[196:199], v[40:43]
	v_mfma_f32_16x16x32_bf16 v[28:31], v[84:87], v[204:207], v[28:31]
	v_mfma_f32_16x16x32_bf16 v[24:27], v[92:95], v[204:207], v[24:27]
	v_mfma_f32_16x16x32_bf16 v[12:15], v[84:87], v[212:215], v[12:15]
	v_mfma_f32_16x16x32_bf16 v[8:11], v[92:95], v[212:215], v[8:11]
	s_setprio 0
	s_setprio 1
	v_mfma_f32_16x16x32_bf16 v[52:55], v[96:99], v[172:175], v[52:55]
	v_mfma_f32_16x16x32_bf16 v[48:51], v[104:107], v[172:175], v[48:51]
	v_mfma_f32_16x16x32_bf16 v[36:39], v[96:99], v[180:183], v[36:39]
	v_mfma_f32_16x16x32_bf16 v[32:35], v[104:107], v[180:183], v[32:35]
	v_mfma_f32_16x16x32_bf16 v[20:23], v[96:99], v[200:203], v[20:23]
	v_mfma_f32_16x16x32_bf16 v[16:19], v[104:107], v[200:203], v[16:19]
	v_mfma_f32_16x16x32_bf16 v[4:7], v[96:99], v[208:211], v[4:7]
	v_mfma_f32_16x16x32_bf16 v[0:3], v[104:107], v[208:211], v[0:3]
	v_mfma_f32_16x16x32_bf16 v[52:55], v[100:103], v[176:179], v[52:55]
	v_mfma_f32_16x16x32_bf16 v[48:51], v[108:111], v[176:179], v[48:51]
	v_mfma_f32_16x16x32_bf16 v[36:39], v[100:103], v[196:199], v[36:39]
	v_mfma_f32_16x16x32_bf16 v[32:35], v[108:111], v[196:199], v[32:35]
	v_mfma_f32_16x16x32_bf16 v[20:23], v[100:103], v[204:207], v[20:23]
	v_mfma_f32_16x16x32_bf16 v[16:19], v[108:111], v[204:207], v[16:19]
	v_mfma_f32_16x16x32_bf16 v[4:7], v[100:103], v[212:215], v[4:7]
	v_mfma_f32_16x16x32_bf16 v[0:3], v[108:111], v[212:215], v[0:3]
	s_setprio 0
	s_add_i32 s50, s50, 2
	s_add_u32 s24, s24, 0x100
	s_addc_u32 s25, s25, 0
	s_add_u32 s48, s48, 0x100
	s_addc_u32 s49, s49, 0
	s_cmp_gt_u32 s50, 13
	s_barrier
	s_cbranch_scc0 .LBB0_535
	s_and_b64 vcc, exec, s[8:9]
	s_cbranch_vccz .LBB0_538
	s_barrier

.LBB0_584:
	ds_read_b128 v[100:103], v193
	ds_read_b128 v[104:107], v193 offset:1024
	ds_read_b128 v[112:115], v193 offset:2048
	ds_read_b128 v[116:119], v193 offset:3072
	ds_read_b128 v[120:123], v194
	ds_read_b128 v[124:127], v194 offset:1024
	ds_read_b128 v[128:131], v194 offset:2048
	ds_read_b128 v[132:135], v194 offset:3072
	s_add_u32 s8, s10, 0x100
	s_addc_u32 s9, s11, 0
	s_cmp_eq_u32 s20, 12
	s_cselect_b32 s15, s81, s9
	s_cselect_b32 s14, s80, s8
	s_cselect_b32 s13, s1, s19
	s_cselect_b32 s12, s17, s18
	v_lshl_add_u64 v[222:223], s[10:11], 0, v[168:169]
	s_add_i32 m0, s53, 0xc000
	ds_read_b128 v[176:179], v195
	ds_read_b128 v[180:183], v195 offset:1024
	ds_read_b128 v[198:201], v195 offset:2048
	ds_read_b128 v[202:205], v195 offset:3072
	ds_read_b128 v[206:209], v195 offset:4096
	ds_read_b128 v[210:213], v195 offset:5120
	ds_read_b128 v[214:217], v195 offset:6144
	ds_read_b128 v[218:221], v195 offset:7168
	global_load_lds_dwordx4 v[222:223], off
	v_lshl_add_u64 v[222:223], s[10:11], 0, v[170:171]
	s_add_i32 m0, s53, 0xe000
	s_nop 0
	global_load_lds_dwordx4 v[222:223], off
	s_waitcnt vmcnt(8)
	s_waitcnt lgkmcnt(0)
	s_barrier
	s_setprio 1
	s_waitcnt lgkmcnt(0)
	v_mfma_f32_16x16x32_bf16 v[156:159], v[176:179], v[100:103], v[156:159]
	v_mfma_f32_16x16x32_bf16 v[148:151], v[198:201], v[100:103], v[148:151]
	v_mfma_f32_16x16x32_bf16 v[140:143], v[206:209], v[100:103], v[140:143]
	v_mfma_f32_16x16x32_bf16 v[108:111], v[214:217], v[100:103], v[108:111]
	v_mfma_f32_16x16x32_bf16 v[60:63], v[176:179], v[112:115], v[60:63]
	v_mfma_f32_16x16x32_bf16 v[52:55], v[198:201], v[112:115], v[52:55]
	v_mfma_f32_16x16x32_bf16 v[44:47], v[206:209], v[112:115], v[44:47]
	v_mfma_f32_16x16x32_bf16 v[36:39], v[214:217], v[112:115], v[36:39]
	v_mfma_f32_16x16x32_bf16 v[156:159], v[180:183], v[104:107], v[156:159]
	v_mfma_f32_16x16x32_bf16 v[148:151], v[202:205], v[104:107], v[148:151]
	v_mfma_f32_16x16x32_bf16 v[140:143], v[210:213], v[104:107], v[140:143]
	v_mfma_f32_16x16x32_bf16 v[108:111], v[218:221], v[104:107], v[108:111]
	v_mfma_f32_16x16x32_bf16 v[60:63], v[180:183], v[116:119], v[60:63]
	v_mfma_f32_16x16x32_bf16 v[52:55], v[202:205], v[116:119], v[52:55]
	v_mfma_f32_16x16x32_bf16 v[44:47], v[210:213], v[116:119], v[44:47]
	v_mfma_f32_16x16x32_bf16 v[36:39], v[218:221], v[116:119], v[36:39]
	s_setprio 0
	s_setprio 1
	v_mfma_f32_16x16x32_bf16 v[152:155], v[176:179], v[120:123], v[152:155]
	v_mfma_f32_16x16x32_bf16 v[144:147], v[198:201], v[120:123], v[144:147]
	v_mfma_f32_16x16x32_bf16 v[136:139], v[206:209], v[120:123], v[136:139]
	v_mfma_f32_16x16x32_bf16 v[96:99], v[214:217], v[120:123], v[96:99]
	v_mfma_f32_16x16x32_bf16 v[56:59], v[176:179], v[128:131], v[56:59]
	v_mfma_f32_16x16x32_bf16 v[48:51], v[198:201], v[128:131], v[48:51]
	v_mfma_f32_16x16x32_bf16 v[40:43], v[206:209], v[128:131], v[40:43]
	v_mfma_f32_16x16x32_bf16 v[32:35], v[214:217], v[128:131], v[32:35]
	v_mfma_f32_16x16x32_bf16 v[152:155], v[180:183], v[124:127], v[152:155]
	v_mfma_f32_16x16x32_bf16 v[144:147], v[202:205], v[124:127], v[144:147]
	v_mfma_f32_16x16x32_bf16 v[136:139], v[210:213], v[124:127], v[136:139]
	v_mfma_f32_16x16x32_bf16 v[96:99], v[218:221], v[124:127], v[96:99]
	v_mfma_f32_16x16x32_bf16 v[56:59], v[180:183], v[132:135], v[56:59]
	v_mfma_f32_16x16x32_bf16 v[48:51], v[202:205], v[132:135], v[48:51]
	v_mfma_f32_16x16x32_bf16 v[40:43], v[210:213], v[132:135], v[40:43]
	v_mfma_f32_16x16x32_bf16 v[32:35], v[218:221], v[132:135], v[32:35]
	s_setprio 0
	s_barrier
	s_add_i32 s10, s91, s52
	v_lshl_add_u64 v[222:223], s[12:13], 0, v[162:163]
	s_mov_b32 m0, s10
	ds_read_b128 v[176:179], v195 offset:16384
	ds_read_b128 v[180:183], v195 offset:17408
	ds_read_b128 v[198:201], v195 offset:18432
	ds_read_b128 v[202:205], v195 offset:19456
	ds_read_b128 v[206:209], v195 offset:20480
	ds_read_b128 v[210:213], v195 offset:21504
	ds_read_b128 v[214:217], v195 offset:22528
	ds_read_b128 v[218:221], v195 offset:23552
	global_load_lds_dwordx4 v[222:223], off
	s_add_i32 m0, s10, 0x2000
	s_add_u32 s10, s12, 0x580000
	v_lshl_add_u64 v[224:225], s[12:13], 0, v[166:167]
	s_addc_u32 s11, s13, 0
	s_add_i32 s21, s60, s52
	global_load_lds_dwordx4 v[224:225], off
	v_lshl_add_u64 v[226:227], s[10:11], 0, v[162:163]
	s_mov_b32 m0, s21
	v_lshl_add_u64 v[228:229], s[14:15], 0, v[164:165]
	global_load_lds_dwordx4 v[226:227], off
	v_lshl_add_u64 v[226:227], s[10:11], 0, v[166:167]
	s_add_i32 m0, s21, 0x2000
	s_nop 0
	global_load_lds_dwordx4 v[226:227], off
	v_lshl_add_u64 v[226:227], s[14:15], 0, v[160:161]
	s_mov_b32 m0, s53
	s_nop 0
	global_load_lds_dwordx4 v[226:227], off
	s_mov_b32 m0, s54
	s_nop 0
	global_load_lds_dwordx4 v[228:229], off
	s_waitcnt vmcnt(8)
	s_waitcnt lgkmcnt(0)
	s_barrier
	s_setprio 1
	s_waitcnt lgkmcnt(0)
	v_mfma_f32_16x16x32_bf16 v[92:95], v[176:179], v[100:103], v[92:95]
	v_mfma_f32_16x16x32_bf16 v[84:87], v[198:201], v[100:103], v[84:87]
	v_mfma_f32_16x16x32_bf16 v[76:79], v[206:209], v[100:103], v[76:79]
	v_mfma_f32_16x16x32_bf16 v[68:71], v[214:217], v[100:103], v[68:71]
	v_mfma_f32_16x16x32_bf16 v[28:31], v[176:179], v[112:115], v[28:31]
	v_mfma_f32_16x16x32_bf16 v[20:23], v[198:201], v[112:115], v[20:23]
	v_mfma_f32_16x16x32_bf16 v[12:15], v[206:209], v[112:115], v[12:15]
	v_mfma_f32_16x16x32_bf16 v[4:7], v[214:217], v[112:115], v[4:7]
	v_mfma_f32_16x16x32_bf16 v[92:95], v[180:183], v[104:107], v[92:95]
	v_mfma_f32_16x16x32_bf16 v[84:87], v[202:205], v[104:107], v[84:87]
	v_mfma_f32_16x16x32_bf16 v[76:79], v[210:213], v[104:107], v[76:79]
	v_mfma_f32_16x16x32_bf16 v[68:71], v[218:221], v[104:107], v[68:71]
	v_mfma_f32_16x16x32_bf16 v[28:31], v[180:183], v[116:119], v[28:31]
	v_mfma_f32_16x16x32_bf16 v[20:23], v[202:205], v[116:119], v[20:23]
	v_mfma_f32_16x16x32_bf16 v[12:15], v[210:213], v[116:119], v[12:15]
	v_mfma_f32_16x16x32_bf16 v[4:7], v[218:221], v[116:119], v[4:7]
	s_setprio 0
	s_setprio 1
	v_mfma_f32_16x16x32_bf16 v[88:91], v[176:179], v[120:123], v[88:91]
	v_mfma_f32_16x16x32_bf16 v[80:83], v[198:201], v[120:123], v[80:83]
	v_mfma_f32_16x16x32_bf16 v[72:75], v[206:209], v[120:123], v[72:75]
	v_mfma_f32_16x16x32_bf16 v[64:67], v[214:217], v[120:123], v[64:67]
	v_mfma_f32_16x16x32_bf16 v[24:27], v[176:179], v[128:131], v[24:27]
	v_mfma_f32_16x16x32_bf16 v[16:19], v[198:201], v[128:131], v[16:19]
	v_mfma_f32_16x16x32_bf16 v[8:11], v[206:209], v[128:131], v[8:11]
	v_mfma_f32_16x16x32_bf16 v[0:3], v[214:217], v[128:131], v[0:3]
	v_mfma_f32_16x16x32_bf16 v[88:91], v[180:183], v[124:127], v[88:91]
	v_mfma_f32_16x16x32_bf16 v[80:83], v[202:205], v[124:127], v[80:83]
	v_mfma_f32_16x16x32_bf16 v[72:75], v[210:213], v[124:127], v[72:75]
	v_mfma_f32_16x16x32_bf16 v[64:67], v[218:221], v[124:127], v[64:67]
	v_mfma_f32_16x16x32_bf16 v[24:27], v[180:183], v[132:135], v[24:27]
	v_mfma_f32_16x16x32_bf16 v[16:19], v[202:205], v[132:135], v[16:19]
	v_mfma_f32_16x16x32_bf16 v[8:11], v[210:213], v[132:135], v[8:11]
	v_mfma_f32_16x16x32_bf16 v[0:3], v[218:221], v[132:135], v[0:3]
	s_setprio 0
	s_barrier
	s_add_i32 s21, 0, 0x18000
	s_add_i32 s22, 0, 0x1c000
	v_add_u32_e32 v116, s21, v188
	v_add_u32_e32 v132, s22, v188
	ds_read_b128 v[100:103], v116
	ds_read_b128 v[104:107], v116 offset:1024
	ds_read_b128 v[112:115], v116 offset:2048
	ds_read_b128 v[116:119], v116 offset:3072
	ds_read_b128 v[120:123], v132
	ds_read_b128 v[124:127], v132 offset:1024
	ds_read_b128 v[128:131], v132 offset:2048
	ds_read_b128 v[132:135], v132 offset:3072
	s_add_u32 s10, s14, 0x3e000
	s_addc_u32 s11, s15, 0
	s_mov_b32 m0, s55
	v_lshl_add_u64 v[230:231], s[10:11], 0, v[160:161]
	ds_read_b128 v[176:179], v195 offset:32768
	ds_read_b128 v[180:183], v195 offset:33792
	ds_read_b128 v[198:201], v195 offset:34816
	ds_read_b128 v[202:205], v195 offset:35840
	ds_read_b128 v[206:209], v195 offset:36864
	ds_read_b128 v[210:213], v195 offset:37888
	ds_read_b128 v[214:217], v195 offset:38912
	ds_read_b128 v[218:221], v195 offset:39936
	global_load_lds_dwordx4 v[230:231], off
	v_lshl_add_u64 v[230:231], s[10:11], 0, v[164:165]
	s_mov_b32 m0, s95
	s_nop 0
	global_load_lds_dwordx4 v[230:231], off
	s_waitcnt vmcnt(8)
	s_waitcnt lgkmcnt(0)
	s_barrier
	s_setprio 1
	s_waitcnt lgkmcnt(0)
	v_mfma_f32_16x16x32_bf16 v[156:159], v[176:179], v[100:103], v[156:159]
	v_mfma_f32_16x16x32_bf16 v[148:151], v[198:201], v[100:103], v[148:151]
	v_mfma_f32_16x16x32_bf16 v[140:143], v[206:209], v[100:103], v[140:143]
	v_mfma_f32_16x16x32_bf16 v[108:111], v[214:217], v[100:103], v[108:111]
	v_mfma_f32_16x16x32_bf16 v[60:63], v[176:179], v[112:115], v[60:63]
	v_mfma_f32_16x16x32_bf16 v[52:55], v[198:201], v[112:115], v[52:55]
	v_mfma_f32_16x16x32_bf16 v[44:47], v[206:209], v[112:115], v[44:47]
	v_mfma_f32_16x16x32_bf16 v[36:39], v[214:217], v[112:115], v[36:39]
	v_mfma_f32_16x16x32_bf16 v[156:159], v[180:183], v[104:107], v[156:159]
	v_mfma_f32_16x16x32_bf16 v[148:151], v[202:205], v[104:107], v[148:151]
	v_mfma_f32_16x16x32_bf16 v[140:143], v[210:213], v[104:107], v[140:143]
	v_mfma_f32_16x16x32_bf16 v[108:111], v[218:221], v[104:107], v[108:111]
	v_mfma_f32_16x16x32_bf16 v[60:63], v[180:183], v[116:119], v[60:63]
	v_mfma_f32_16x16x32_bf16 v[52:55], v[202:205], v[116:119], v[52:55]
	v_mfma_f32_16x16x32_bf16 v[44:47], v[210:213], v[116:119], v[44:47]
	v_mfma_f32_16x16x32_bf16 v[36:39], v[218:221], v[116:119], v[36:39]
	s_setprio 0
	s_setprio 1
	v_mfma_f32_16x16x32_bf16 v[152:155], v[176:179], v[120:123], v[152:155]
	v_mfma_f32_16x16x32_bf16 v[144:147], v[198:201], v[120:123], v[144:147]
	v_mfma_f32_16x16x32_bf16 v[136:139], v[206:209], v[120:123], v[136:139]
	v_mfma_f32_16x16x32_bf16 v[96:99], v[214:217], v[120:123], v[96:99]
	v_mfma_f32_16x16x32_bf16 v[56:59], v[176:179], v[128:131], v[56:59]
	v_mfma_f32_16x16x32_bf16 v[48:51], v[198:201], v[128:131], v[48:51]
	v_mfma_f32_16x16x32_bf16 v[40:43], v[206:209], v[128:131], v[40:43]
	v_mfma_f32_16x16x32_bf16 v[32:35], v[214:217], v[128:131], v[32:35]
	v_mfma_f32_16x16x32_bf16 v[152:155], v[180:183], v[124:127], v[152:155]
	v_mfma_f32_16x16x32_bf16 v[144:147], v[202:205], v[124:127], v[144:147]
	v_mfma_f32_16x16x32_bf16 v[136:139], v[210:213], v[124:127], v[136:139]
	v_mfma_f32_16x16x32_bf16 v[96:99], v[218:221], v[124:127], v[96:99]
	v_mfma_f32_16x16x32_bf16 v[56:59], v[180:183], v[132:135], v[56:59]
	v_mfma_f32_16x16x32_bf16 v[48:51], v[202:205], v[132:135], v[48:51]
	v_mfma_f32_16x16x32_bf16 v[40:43], v[210:213], v[132:135], v[40:43]
	v_mfma_f32_16x16x32_bf16 v[32:35], v[218:221], v[132:135], v[32:35]
	s_setprio 0
	s_barrier
	s_add_i32 s10, s21, s52
	v_lshl_add_u64 v[222:223], v[222:223], 0, s[56:57]
	s_mov_b32 m0, s10
	ds_read_b128 v[176:179], v195 offset:49152
	ds_read_b128 v[180:183], v195 offset:50176
	ds_read_b128 v[198:201], v195 offset:51200
	ds_read_b128 v[202:205], v195 offset:52224
	ds_read_b128 v[206:209], v195 offset:53248
	ds_read_b128 v[210:213], v195 offset:54272
	ds_read_b128 v[214:217], v195 offset:55296
	ds_read_b128 v[218:221], v195 offset:56320
	global_load_lds_dwordx4 v[222:223], off
	s_add_i32 m0, s10, 0x2000
	s_add_u32 s10, s12, 0x580080
	v_lshl_add_u64 v[222:223], v[224:225], 0, s[56:57]
	s_addc_u32 s11, s13, 0
	s_add_i32 s12, s22, s52
	global_load_lds_dwordx4 v[222:223], off
	v_lshl_add_u64 v[222:223], s[10:11], 0, v[162:163]
	s_mov_b32 m0, s12
	s_nop 0
	global_load_lds_dwordx4 v[222:223], off
	v_lshl_add_u64 v[222:223], s[10:11], 0, v[166:167]
	s_add_i32 m0, s12, 0x2000
	s_nop 0
	global_load_lds_dwordx4 v[222:223], off
	v_lshl_add_u64 v[222:223], v[226:227], 0, s[56:57]
	s_mov_b32 m0, s89
	s_nop 0
	global_load_lds_dwordx4 v[222:223], off
	v_lshl_add_u64 v[222:223], v[228:229], 0, s[56:57]
	s_mov_b32 m0, s90
	s_nop 0
	global_load_lds_dwordx4 v[222:223], off
	s_waitcnt vmcnt(8)
	s_waitcnt lgkmcnt(0)
	s_barrier
	s_setprio 1
	s_waitcnt lgkmcnt(0)
	v_mfma_f32_16x16x32_bf16 v[92:95], v[176:179], v[100:103], v[92:95]
	v_mfma_f32_16x16x32_bf16 v[84:87], v[198:201], v[100:103], v[84:87]
	v_mfma_f32_16x16x32_bf16 v[76:79], v[206:209], v[100:103], v[76:79]
	v_mfma_f32_16x16x32_bf16 v[68:71], v[214:217], v[100:103], v[68:71]
	v_mfma_f32_16x16x32_bf16 v[28:31], v[176:179], v[112:115], v[28:31]
	v_mfma_f32_16x16x32_bf16 v[20:23], v[198:201], v[112:115], v[20:23]
	v_mfma_f32_16x16x32_bf16 v[12:15], v[206:209], v[112:115], v[12:15]
	v_mfma_f32_16x16x32_bf16 v[4:7], v[214:217], v[112:115], v[4:7]
	v_mfma_f32_16x16x32_bf16 v[92:95], v[180:183], v[104:107], v[92:95]
	v_mfma_f32_16x16x32_bf16 v[84:87], v[202:205], v[104:107], v[84:87]
	v_mfma_f32_16x16x32_bf16 v[76:79], v[210:213], v[104:107], v[76:79]
	v_mfma_f32_16x16x32_bf16 v[68:71], v[218:221], v[104:107], v[68:71]
	v_mfma_f32_16x16x32_bf16 v[28:31], v[180:183], v[116:119], v[28:31]
	v_mfma_f32_16x16x32_bf16 v[20:23], v[202:205], v[116:119], v[20:23]
	v_mfma_f32_16x16x32_bf16 v[12:15], v[210:213], v[116:119], v[12:15]
	v_mfma_f32_16x16x32_bf16 v[4:7], v[218:221], v[116:119], v[4:7]
	s_setprio 0
	s_setprio 1
	v_mfma_f32_16x16x32_bf16 v[88:91], v[176:179], v[120:123], v[88:91]
	v_mfma_f32_16x16x32_bf16 v[80:83], v[198:201], v[120:123], v[80:83]
	v_mfma_f32_16x16x32_bf16 v[72:75], v[206:209], v[120:123], v[72:75]
	v_mfma_f32_16x16x32_bf16 v[64:67], v[214:217], v[120:123], v[64:67]
	v_mfma_f32_16x16x32_bf16 v[24:27], v[176:179], v[128:131], v[24:27]
	v_mfma_f32_16x16x32_bf16 v[16:19], v[198:201], v[128:131], v[16:19]
	v_mfma_f32_16x16x32_bf16 v[8:11], v[206:209], v[128:131], v[8:11]
	v_mfma_f32_16x16x32_bf16 v[0:3], v[214:217], v[128:131], v[0:3]
	v_mfma_f32_16x16x32_bf16 v[88:91], v[180:183], v[124:127], v[88:91]
	v_mfma_f32_16x16x32_bf16 v[80:83], v[202:205], v[124:127], v[80:83]
	v_mfma_f32_16x16x32_bf16 v[72:75], v[210:213], v[124:127], v[72:75]
	v_mfma_f32_16x16x32_bf16 v[64:67], v[218:221], v[124:127], v[64:67]
	v_mfma_f32_16x16x32_bf16 v[24:27], v[180:183], v[132:135], v[24:27]
	v_mfma_f32_16x16x32_bf16 v[16:19], v[202:205], v[132:135], v[16:19]
	v_mfma_f32_16x16x32_bf16 v[8:11], v[210:213], v[132:135], v[8:11]
	v_mfma_f32_16x16x32_bf16 v[0:3], v[218:221], v[132:135], v[0:3]
	s_setprio 0
	s_add_i32 s20, s20, 2
	s_add_u32 s18, s18, 0x100
	s_addc_u32 s19, s19, 0
	s_cmp_gt_u32 s20, 13
	s_mov_b64 s[10:11], s[8:9]
	s_barrier
	s_cbranch_scc0 .LBB0_584
	v_readlane_b32 s8, v254, 2
	v_readlane_b32 s9, v254, 3
	s_and_b64 vcc, exec, s[8:9]
	s_cbranch_vccz .LBB0_587
	s_barrier

.LBB0_656:
	ds_read_b128 v[140:143], v149
	ds_read_b128 v[152:155], v149 offset:1024
	ds_read_b128 v[156:159], v149 offset:2048
	ds_read_b128 v[160:163], v149 offset:3072
	ds_read_b128 v[164:167], v150
	ds_read_b128 v[168:171], v150 offset:1024
	ds_read_b128 v[172:175], v150 offset:2048
	ds_read_b128 v[176:179], v150 offset:3072
	s_add_u32 s24, s22, 0xfff50080
	s_addc_u32 s25, s23, -1
	s_cmp_eq_u32 s49, 40
	s_cselect_b32 s27, s5, s25
	s_cselect_b32 s26, s4, s24
	s_cselect_b32 s25, s21, s48
	s_cselect_b32 s24, s20, s47
	v_lshl_add_u64 v[144:145], s[22:23], 0, v[132:133]
	s_add_i32 m0, s31, 0xc000
	ds_read_b128 v[180:183], v151
	ds_read_b128 v[186:189], v151 offset:1024
	ds_read_b128 v[190:193], v151 offset:2048
	ds_read_b128 v[194:197], v151 offset:3072
	ds_read_b128 v[198:201], v151 offset:4096
	ds_read_b128 v[202:205], v151 offset:5120
	ds_read_b128 v[206:209], v151 offset:6144
	ds_read_b128 v[210:213], v151 offset:7168
	global_load_lds_dwordx4 v[144:145], off
	v_lshl_add_u64 v[144:145], s[22:23], 0, v[134:135]
	s_add_i32 m0, s31, 0xe000
	s_nop 0
	global_load_lds_dwordx4 v[144:145], off
	s_waitcnt vmcnt(8)
	s_waitcnt lgkmcnt(0)
	s_barrier
	s_setprio 1
	s_waitcnt lgkmcnt(0)
	v_mfma_f32_16x16x32_bf16 v[124:127], v[140:143], v[180:183], v[124:127]
	v_mfma_f32_16x16x32_bf16 v[120:123], v[156:159], v[180:183], v[120:123]
	v_mfma_f32_16x16x32_bf16 v[108:111], v[140:143], v[190:193], v[108:111]
	v_mfma_f32_16x16x32_bf16 v[104:107], v[156:159], v[190:193], v[104:107]
	v_mfma_f32_16x16x32_bf16 v[92:95], v[140:143], v[198:201], v[92:95]
	v_mfma_f32_16x16x32_bf16 v[88:91], v[156:159], v[198:201], v[88:91]
	v_mfma_f32_16x16x32_bf16 v[76:79], v[140:143], v[206:209], v[76:79]
	v_mfma_f32_16x16x32_bf16 v[72:75], v[156:159], v[206:209], v[72:75]
	v_mfma_f32_16x16x32_bf16 v[124:127], v[152:155], v[186:189], v[124:127]
	v_mfma_f32_16x16x32_bf16 v[120:123], v[160:163], v[186:189], v[120:123]
	v_mfma_f32_16x16x32_bf16 v[108:111], v[152:155], v[194:197], v[108:111]
	v_mfma_f32_16x16x32_bf16 v[104:107], v[160:163], v[194:197], v[104:107]
	v_mfma_f32_16x16x32_bf16 v[92:95], v[152:155], v[202:205], v[92:95]
	v_mfma_f32_16x16x32_bf16 v[88:91], v[160:163], v[202:205], v[88:91]
	v_mfma_f32_16x16x32_bf16 v[76:79], v[152:155], v[210:213], v[76:79]
	v_mfma_f32_16x16x32_bf16 v[72:75], v[160:163], v[210:213], v[72:75]
	s_setprio 0
	s_setprio 1
	v_mfma_f32_16x16x32_bf16 v[116:119], v[164:167], v[180:183], v[116:119]
	v_mfma_f32_16x16x32_bf16 v[112:115], v[172:175], v[180:183], v[112:115]
	v_mfma_f32_16x16x32_bf16 v[100:103], v[164:167], v[190:193], v[100:103]
	v_mfma_f32_16x16x32_bf16 v[96:99], v[172:175], v[190:193], v[96:99]
	v_mfma_f32_16x16x32_bf16 v[84:87], v[164:167], v[198:201], v[84:87]
	v_mfma_f32_16x16x32_bf16 v[80:83], v[172:175], v[198:201], v[80:83]
	v_mfma_f32_16x16x32_bf16 v[68:71], v[164:167], v[206:209], v[68:71]
	v_mfma_f32_16x16x32_bf16 v[64:67], v[172:175], v[206:209], v[64:67]
	v_mfma_f32_16x16x32_bf16 v[116:119], v[168:171], v[186:189], v[116:119]
	v_mfma_f32_16x16x32_bf16 v[112:115], v[176:179], v[186:189], v[112:115]
	v_mfma_f32_16x16x32_bf16 v[100:103], v[168:171], v[194:197], v[100:103]
	v_mfma_f32_16x16x32_bf16 v[96:99], v[176:179], v[194:197], v[96:99]
	v_mfma_f32_16x16x32_bf16 v[84:87], v[168:171], v[202:205], v[84:87]
	v_mfma_f32_16x16x32_bf16 v[80:83], v[176:179], v[202:205], v[80:83]
	v_mfma_f32_16x16x32_bf16 v[68:71], v[168:171], v[210:213], v[68:71]
	v_mfma_f32_16x16x32_bf16 v[64:67], v[176:179], v[210:213], v[64:67]
	s_setprio 0
	s_barrier
	s_add_i32 s50, s41, s30
	v_lshl_add_u64 v[144:145], s[24:25], 0, v[128:129]
	s_mov_b32 m0, s50
	ds_read_b128 v[180:183], v151 offset:16384
	ds_read_b128 v[186:189], v151 offset:17408
	ds_read_b128 v[190:193], v151 offset:18432
	ds_read_b128 v[194:197], v151 offset:19456
	ds_read_b128 v[198:201], v151 offset:20480
	ds_read_b128 v[202:205], v151 offset:21504
	ds_read_b128 v[206:209], v151 offset:22528
	ds_read_b128 v[210:213], v151 offset:23552
	global_load_lds_dwordx4 v[144:145], off
	s_add_i32 m0, s50, 0x2000
	s_add_u32 s50, s24, 0xb0000
	v_lshl_add_u64 v[214:215], s[24:25], 0, v[130:131]
	s_addc_u32 s51, s25, 0
	s_add_i32 s52, s42, s30
	global_load_lds_dwordx4 v[214:215], off
	v_lshl_add_u64 v[216:217], s[50:51], 0, v[128:129]
	s_mov_b32 m0, s52
	v_lshl_add_u64 v[218:219], s[26:27], 0, v[130:131]
	global_load_lds_dwordx4 v[216:217], off
	v_lshl_add_u64 v[216:217], s[50:51], 0, v[130:131]
	s_add_i32 m0, s52, 0x2000
	s_nop 0
	global_load_lds_dwordx4 v[216:217], off
	v_lshl_add_u64 v[216:217], s[26:27], 0, v[128:129]
	s_mov_b32 m0, s31
	s_nop 0
	global_load_lds_dwordx4 v[216:217], off
	s_mov_b32 m0, s34
	s_nop 0
	global_load_lds_dwordx4 v[218:219], off
	s_waitcnt vmcnt(8)
	s_waitcnt lgkmcnt(0)
	s_barrier
	s_setprio 1
	s_waitcnt lgkmcnt(0)
	v_mfma_f32_16x16x32_bf16 v[60:63], v[140:143], v[180:183], v[60:63]
	v_mfma_f32_16x16x32_bf16 v[56:59], v[156:159], v[180:183], v[56:59]
	v_mfma_f32_16x16x32_bf16 v[44:47], v[140:143], v[190:193], v[44:47]
	v_mfma_f32_16x16x32_bf16 v[40:43], v[156:159], v[190:193], v[40:43]
	v_mfma_f32_16x16x32_bf16 v[28:31], v[140:143], v[198:201], v[28:31]
	v_mfma_f32_16x16x32_bf16 v[24:27], v[156:159], v[198:201], v[24:27]
	v_mfma_f32_16x16x32_bf16 v[12:15], v[140:143], v[206:209], v[12:15]
	v_mfma_f32_16x16x32_bf16 v[8:11], v[156:159], v[206:209], v[8:11]
	v_mfma_f32_16x16x32_bf16 v[60:63], v[152:155], v[186:189], v[60:63]
	v_mfma_f32_16x16x32_bf16 v[56:59], v[160:163], v[186:189], v[56:59]
	v_mfma_f32_16x16x32_bf16 v[44:47], v[152:155], v[194:197], v[44:47]
	v_mfma_f32_16x16x32_bf16 v[40:43], v[160:163], v[194:197], v[40:43]
	v_mfma_f32_16x16x32_bf16 v[28:31], v[152:155], v[202:205], v[28:31]
	v_mfma_f32_16x16x32_bf16 v[24:27], v[160:163], v[202:205], v[24:27]
	v_mfma_f32_16x16x32_bf16 v[12:15], v[152:155], v[210:213], v[12:15]
	v_mfma_f32_16x16x32_bf16 v[8:11], v[160:163], v[210:213], v[8:11]
	s_setprio 0
	s_setprio 1
	v_mfma_f32_16x16x32_bf16 v[52:55], v[164:167], v[180:183], v[52:55]
	v_mfma_f32_16x16x32_bf16 v[48:51], v[172:175], v[180:183], v[48:51]
	v_mfma_f32_16x16x32_bf16 v[36:39], v[164:167], v[190:193], v[36:39]
	v_mfma_f32_16x16x32_bf16 v[32:35], v[172:175], v[190:193], v[32:35]
	v_mfma_f32_16x16x32_bf16 v[20:23], v[164:167], v[198:201], v[20:23]
	v_mfma_f32_16x16x32_bf16 v[16:19], v[172:175], v[198:201], v[16:19]
	v_mfma_f32_16x16x32_bf16 v[4:7], v[164:167], v[206:209], v[4:7]
	v_mfma_f32_16x16x32_bf16 v[0:3], v[172:175], v[206:209], v[0:3]
	v_mfma_f32_16x16x32_bf16 v[52:55], v[168:171], v[186:189], v[52:55]
	v_mfma_f32_16x16x32_bf16 v[48:51], v[176:179], v[186:189], v[48:51]
	v_mfma_f32_16x16x32_bf16 v[36:39], v[168:171], v[194:197], v[36:39]
	v_mfma_f32_16x16x32_bf16 v[32:35], v[176:179], v[194:197], v[32:35]
	v_mfma_f32_16x16x32_bf16 v[20:23], v[168:171], v[202:205], v[20:23]
	v_mfma_f32_16x16x32_bf16 v[16:19], v[176:179], v[202:205], v[16:19]
	v_mfma_f32_16x16x32_bf16 v[4:7], v[168:171], v[210:213], v[4:7]
	v_mfma_f32_16x16x32_bf16 v[0:3], v[176:179], v[210:213], v[0:3]
	s_setprio 0
	s_barrier
	s_add_i32 s50, 0, 0x18000
	s_add_i32 s51, 0, 0x1c000
	v_add_u32_e32 v160, s50, v147
	v_add_u32_e32 v176, s51, v147
	ds_read_b128 v[140:143], v160
	ds_read_b128 v[152:155], v160 offset:1024
	ds_read_b128 v[156:159], v160 offset:2048
	ds_read_b128 v[160:163], v160 offset:3072
	ds_read_b128 v[164:167], v176
	ds_read_b128 v[168:171], v176 offset:1024
	ds_read_b128 v[172:175], v176 offset:2048
	ds_read_b128 v[176:179], v176 offset:3072
	s_add_u32 s26, s26, 0xb0000
	s_addc_u32 s27, s27, 0
	s_mov_b32 m0, s35
	v_lshl_add_u64 v[220:221], s[26:27], 0, v[128:129]
	ds_read_b128 v[180:183], v151 offset:32768
	ds_read_b128 v[186:189], v151 offset:33792
	ds_read_b128 v[190:193], v151 offset:34816
	ds_read_b128 v[194:197], v151 offset:35840
	ds_read_b128 v[198:201], v151 offset:36864
	ds_read_b128 v[202:205], v151 offset:37888
	ds_read_b128 v[206:209], v151 offset:38912
	ds_read_b128 v[210:213], v151 offset:39936
	global_load_lds_dwordx4 v[220:221], off
	v_lshl_add_u64 v[220:221], s[26:27], 0, v[130:131]
	s_mov_b32 m0, s36
	s_nop 0
	global_load_lds_dwordx4 v[220:221], off
	s_waitcnt vmcnt(8)
	s_waitcnt lgkmcnt(0)
	s_barrier
	s_setprio 1
	s_waitcnt lgkmcnt(0)
	v_mfma_f32_16x16x32_bf16 v[124:127], v[140:143], v[180:183], v[124:127]
	v_mfma_f32_16x16x32_bf16 v[120:123], v[156:159], v[180:183], v[120:123]
	v_mfma_f32_16x16x32_bf16 v[108:111], v[140:143], v[190:193], v[108:111]
	v_mfma_f32_16x16x32_bf16 v[104:107], v[156:159], v[190:193], v[104:107]
	v_mfma_f32_16x16x32_bf16 v[92:95], v[140:143], v[198:201], v[92:95]
	v_mfma_f32_16x16x32_bf16 v[88:91], v[156:159], v[198:201], v[88:91]
	v_mfma_f32_16x16x32_bf16 v[76:79], v[140:143], v[206:209], v[76:79]
	v_mfma_f32_16x16x32_bf16 v[72:75], v[156:159], v[206:209], v[72:75]
	v_mfma_f32_16x16x32_bf16 v[124:127], v[152:155], v[186:189], v[124:127]
	v_mfma_f32_16x16x32_bf16 v[120:123], v[160:163], v[186:189], v[120:123]
	v_mfma_f32_16x16x32_bf16 v[108:111], v[152:155], v[194:197], v[108:111]
	v_mfma_f32_16x16x32_bf16 v[104:107], v[160:163], v[194:197], v[104:107]
	v_mfma_f32_16x16x32_bf16 v[92:95], v[152:155], v[202:205], v[92:95]
	v_mfma_f32_16x16x32_bf16 v[88:91], v[160:163], v[202:205], v[88:91]
	v_mfma_f32_16x16x32_bf16 v[76:79], v[152:155], v[210:213], v[76:79]
	v_mfma_f32_16x16x32_bf16 v[72:75], v[160:163], v[210:213], v[72:75]
	s_setprio 0
	s_setprio 1
	v_mfma_f32_16x16x32_bf16 v[116:119], v[164:167], v[180:183], v[116:119]
	v_mfma_f32_16x16x32_bf16 v[112:115], v[172:175], v[180:183], v[112:115]
	v_mfma_f32_16x16x32_bf16 v[100:103], v[164:167], v[190:193], v[100:103]
	v_mfma_f32_16x16x32_bf16 v[96:99], v[172:175], v[190:193], v[96:99]
	v_mfma_f32_16x16x32_bf16 v[84:87], v[164:167], v[198:201], v[84:87]
	v_mfma_f32_16x16x32_bf16 v[80:83], v[172:175], v[198:201], v[80:83]
	v_mfma_f32_16x16x32_bf16 v[68:71], v[164:167], v[206:209], v[68:71]
	v_mfma_f32_16x16x32_bf16 v[64:67], v[172:175], v[206:209], v[64:67]
	v_mfma_f32_16x16x32_bf16 v[116:119], v[168:171], v[186:189], v[116:119]
	v_mfma_f32_16x16x32_bf16 v[112:115], v[176:179], v[186:189], v[112:115]
	v_mfma_f32_16x16x32_bf16 v[100:103], v[168:171], v[194:197], v[100:103]
	v_mfma_f32_16x16x32_bf16 v[96:99], v[176:179], v[194:197], v[96:99]
	v_mfma_f32_16x16x32_bf16 v[84:87], v[168:171], v[202:205], v[84:87]
	v_mfma_f32_16x16x32_bf16 v[80:83], v[176:179], v[202:205], v[80:83]
	v_mfma_f32_16x16x32_bf16 v[68:71], v[168:171], v[210:213], v[68:71]
	v_mfma_f32_16x16x32_bf16 v[64:67], v[176:179], v[210:213], v[64:67]
	s_setprio 0
	s_barrier
	s_add_i32 s26, s50, s30
	v_lshl_add_u64 v[144:145], v[144:145], 0, s[6:7]
	s_mov_b32 m0, s26
	ds_read_b128 v[180:183], v151 offset:49152
	ds_read_b128 v[186:189], v151 offset:50176
	ds_read_b128 v[190:193], v151 offset:51200
	ds_read_b128 v[194:197], v151 offset:52224
	ds_read_b128 v[198:201], v151 offset:53248
	ds_read_b128 v[202:205], v151 offset:54272
	ds_read_b128 v[206:209], v151 offset:55296
	ds_read_b128 v[210:213], v151 offset:56320
	global_load_lds_dwordx4 v[144:145], off
	s_add_i32 m0, s26, 0x2000
	s_add_u32 s24, s24, 0xb0080
	v_lshl_add_u64 v[144:145], v[214:215], 0, s[6:7]
	s_addc_u32 s25, s25, 0
	s_add_i32 s26, s51, s30
	global_load_lds_dwordx4 v[144:145], off
	v_lshl_add_u64 v[144:145], s[24:25], 0, v[128:129]
	s_mov_b32 m0, s26
	s_nop 0
	global_load_lds_dwordx4 v[144:145], off
	v_lshl_add_u64 v[144:145], s[24:25], 0, v[130:131]
	s_add_i32 m0, s26, 0x2000
	s_nop 0
	global_load_lds_dwordx4 v[144:145], off
	v_lshl_add_u64 v[144:145], v[216:217], 0, s[6:7]
	s_mov_b32 m0, s38
	s_nop 0
	global_load_lds_dwordx4 v[144:145], off
	v_lshl_add_u64 v[144:145], v[218:219], 0, s[6:7]
	s_mov_b32 m0, s39
	s_nop 0
	global_load_lds_dwordx4 v[144:145], off
	s_waitcnt vmcnt(8)
	s_waitcnt lgkmcnt(0)
	s_barrier
	s_setprio 1
	s_waitcnt lgkmcnt(0)
	v_mfma_f32_16x16x32_bf16 v[60:63], v[140:143], v[180:183], v[60:63]
	v_mfma_f32_16x16x32_bf16 v[56:59], v[156:159], v[180:183], v[56:59]
	v_mfma_f32_16x16x32_bf16 v[44:47], v[140:143], v[190:193], v[44:47]
	v_mfma_f32_16x16x32_bf16 v[40:43], v[156:159], v[190:193], v[40:43]
	v_mfma_f32_16x16x32_bf16 v[28:31], v[140:143], v[198:201], v[28:31]
	v_mfma_f32_16x16x32_bf16 v[24:27], v[156:159], v[198:201], v[24:27]
	v_mfma_f32_16x16x32_bf16 v[12:15], v[140:143], v[206:209], v[12:15]
	v_mfma_f32_16x16x32_bf16 v[8:11], v[156:159], v[206:209], v[8:11]
	v_mfma_f32_16x16x32_bf16 v[60:63], v[152:155], v[186:189], v[60:63]
	v_mfma_f32_16x16x32_bf16 v[56:59], v[160:163], v[186:189], v[56:59]
	v_mfma_f32_16x16x32_bf16 v[44:47], v[152:155], v[194:197], v[44:47]
	v_mfma_f32_16x16x32_bf16 v[40:43], v[160:163], v[194:197], v[40:43]
	v_mfma_f32_16x16x32_bf16 v[28:31], v[152:155], v[202:205], v[28:31]
	v_mfma_f32_16x16x32_bf16 v[24:27], v[160:163], v[202:205], v[24:27]
	v_mfma_f32_16x16x32_bf16 v[12:15], v[152:155], v[210:213], v[12:15]
	v_mfma_f32_16x16x32_bf16 v[8:11], v[160:163], v[210:213], v[8:11]
	s_setprio 0
	s_setprio 1
	v_mfma_f32_16x16x32_bf16 v[52:55], v[164:167], v[180:183], v[52:55]
	v_mfma_f32_16x16x32_bf16 v[48:51], v[172:175], v[180:183], v[48:51]
	v_mfma_f32_16x16x32_bf16 v[36:39], v[164:167], v[190:193], v[36:39]
	v_mfma_f32_16x16x32_bf16 v[32:35], v[172:175], v[190:193], v[32:35]
	v_mfma_f32_16x16x32_bf16 v[20:23], v[164:167], v[198:201], v[20:23]
	v_mfma_f32_16x16x32_bf16 v[16:19], v[172:175], v[198:201], v[16:19]
	v_mfma_f32_16x16x32_bf16 v[4:7], v[164:167], v[206:209], v[4:7]
	v_mfma_f32_16x16x32_bf16 v[0:3], v[172:175], v[206:209], v[0:3]
	v_mfma_f32_16x16x32_bf16 v[52:55], v[168:171], v[186:189], v[52:55]
	v_mfma_f32_16x16x32_bf16 v[48:51], v[176:179], v[186:189], v[48:51]
	v_mfma_f32_16x16x32_bf16 v[36:39], v[168:171], v[194:197], v[36:39]
	v_mfma_f32_16x16x32_bf16 v[32:35], v[176:179], v[194:197], v[32:35]
	v_mfma_f32_16x16x32_bf16 v[20:23], v[168:171], v[202:205], v[20:23]
	v_mfma_f32_16x16x32_bf16 v[16:19], v[176:179], v[202:205], v[16:19]
	v_mfma_f32_16x16x32_bf16 v[4:7], v[168:171], v[210:213], v[4:7]
	v_mfma_f32_16x16x32_bf16 v[0:3], v[176:179], v[210:213], v[0:3]
	s_setprio 0
	s_add_i32 s49, s49, 2
	s_add_u32 s22, s22, 0x100
	s_addc_u32 s23, s23, 0
	s_add_u32 s47, s47, 0x100
	s_addc_u32 s48, s48, 0
	s_cmp_gt_u32 s49, 41
	s_barrier
	s_cbranch_scc0 .LBB0_656
	s_and_b64 vcc, exec, s[8:9]
	s_cbranch_vccz .LBB0_659
	s_barrier
